# v83 + mout_item: Cin/K tile staging loads issued 8 at a time into distinct registers instead of 23 serialized load-wait-write steps
# speedup vs baseline: 1.0198x; 1.0037x over previous
.LBB1_99:
	v_mul_f32_e32 v116, v33, v35
	v_cvt_pk_bf16_f32 v32, v32, v36
	v_cvt_pk_bf16_f32 v33, v41, v38
	ds_write_b64 v43, v[32:33] offset:4576
	v_add_u32_e32 v56, v158, v42
	v_mul_f32_e32 v110, v45, v47
	v_mul_f32_e32 v114, v44, v46
	v_mul_f32_e32 v112, v34, v37
	s_waitcnt lgkmcnt(0)
	s_barrier
	ds_read_b128 v[32:35], v56
	ds_read_b128 v[36:39], v56 offset:64
	ds_read_b128 v[40:43], v56 offset:128
	ds_read_b128 v[88:91], v56 offset:192
	ds_read_b128 v[44:47], v56 offset:4352
	ds_read_b128 v[48:51], v56 offset:4416
	ds_read_b128 v[52:55], v56 offset:4480
	ds_read_b128 v[92:95], v56 offset:4544
	ds_read_b128 v[56:59], v157 offset:34816
	ds_read_b128 v[60:63], v157 offset:39168
	ds_read_b128 v[64:67], v157 offset:43520
	ds_read_b128 v[68:71], v157 offset:47872
	ds_read_b128 v[72:75], v157 offset:52224
	ds_read_b128 v[76:79], v157 offset:56576
	ds_read_b128 v[80:83], v157 offset:60928
	ds_read_b128 v[84:87], v157 offset:65280
	s_setprio 1
	s_waitcnt lgkmcnt(7)
	v_mfma_f32_16x16x32_bf16 v[96:99], v[56:59], v[32:35], 0
	v_mfma_f32_16x16x32_bf16 v[56:59], v[56:59], v[44:47], 0
	s_waitcnt lgkmcnt(6)
	v_mfma_f32_16x16x32_bf16 v[100:103], v[60:63], v[32:35], 0
	v_mfma_f32_16x16x32_bf16 v[60:63], v[60:63], v[44:47], 0
	s_waitcnt lgkmcnt(5)
	v_mfma_f32_16x16x32_bf16 v[118:121], v[64:67], v[32:35], 0
	v_mfma_f32_16x16x32_bf16 v[64:67], v[64:67], v[44:47], 0
	s_waitcnt lgkmcnt(4)
	v_mfma_f32_16x16x32_bf16 v[122:125], v[68:71], v[32:35], 0
	v_mfma_f32_16x16x32_bf16 v[68:71], v[68:71], v[44:47], 0
	s_waitcnt lgkmcnt(3)
	v_mfma_f32_16x16x32_bf16 v[130:133], v[72:75], v[32:35], 0
	v_mfma_f32_16x16x32_bf16 v[72:75], v[72:75], v[44:47], 0
	s_waitcnt lgkmcnt(2)
	v_mfma_f32_16x16x32_bf16 v[134:137], v[76:79], v[32:35], 0
	v_mfma_f32_16x16x32_bf16 v[76:79], v[76:79], v[44:47], 0
	s_waitcnt lgkmcnt(1)
	v_mfma_f32_16x16x32_bf16 v[138:141], v[80:83], v[32:35], 0
	v_mfma_f32_16x16x32_bf16 v[80:83], v[80:83], v[44:47], 0
	s_waitcnt lgkmcnt(0)
	v_mfma_f32_16x16x32_bf16 v[32:35], v[84:87], v[32:35], 0
	v_mfma_f32_16x16x32_bf16 v[44:47], v[84:87], v[44:47], 0
	s_setprio 0
	ds_read_b128 v[84:87], v157 offset:34880
	ds_read_b128 v[142:145], v157 offset:39232
	ds_read_b128 v[146:149], v157 offset:43584
	ds_read_b128 v[150:153], v157 offset:47936
	ds_read_b128 v[158:161], v157 offset:52288
	ds_read_b128 v[188:191], v157 offset:56640
	ds_read_b128 v[192:195], v157 offset:60992
	ds_read_b128 v[196:199], v157 offset:65344
	s_setprio 1
	s_waitcnt lgkmcnt(7)
	v_mfma_f32_16x16x32_bf16 v[96:99], v[84:87], v[36:39], v[96:99]
	v_mfma_f32_16x16x32_bf16 v[56:59], v[84:87], v[48:51], v[56:59]
	s_waitcnt lgkmcnt(6)
	v_mfma_f32_16x16x32_bf16 v[84:87], v[142:145], v[36:39], v[100:103]
	v_mfma_f32_16x16x32_bf16 v[60:63], v[142:145], v[48:51], v[60:63]
	s_waitcnt lgkmcnt(5)
	v_mfma_f32_16x16x32_bf16 v[100:103], v[146:149], v[36:39], v[118:121]
	v_mfma_f32_16x16x32_bf16 v[64:67], v[146:149], v[48:51], v[64:67]
	s_waitcnt lgkmcnt(4)
	v_mfma_f32_16x16x32_bf16 v[118:121], v[150:153], v[36:39], v[122:125]
	v_mfma_f32_16x16x32_bf16 v[68:71], v[150:153], v[48:51], v[68:71]
	s_waitcnt lgkmcnt(3)
	v_mfma_f32_16x16x32_bf16 v[122:125], v[158:161], v[36:39], v[130:133]
	v_mfma_f32_16x16x32_bf16 v[72:75], v[158:161], v[48:51], v[72:75]
	s_waitcnt lgkmcnt(2)
	v_mfma_f32_16x16x32_bf16 v[130:133], v[188:191], v[36:39], v[134:137]
	v_mfma_f32_16x16x32_bf16 v[76:79], v[188:191], v[48:51], v[76:79]
	s_waitcnt lgkmcnt(1)
	v_mfma_f32_16x16x32_bf16 v[134:137], v[192:195], v[36:39], v[138:141]
	v_mfma_f32_16x16x32_bf16 v[80:83], v[192:195], v[48:51], v[80:83]
	s_waitcnt lgkmcnt(0)
	v_mfma_f32_16x16x32_bf16 v[32:35], v[196:199], v[36:39], v[32:35]
	v_mfma_f32_16x16x32_bf16 v[36:39], v[196:199], v[48:51], v[44:47]
	s_setprio 0
	s_nop 1
	ds_read_b128 v[44:47], v157 offset:34944
	ds_read_b128 v[48:51], v157 offset:39296
	ds_read_b128 v[138:141], v157 offset:43648
	ds_read_b128 v[142:145], v157 offset:48000
	ds_read_b128 v[146:149], v157 offset:52352
	ds_read_b128 v[150:153], v157 offset:56704
	ds_read_b128 v[158:161], v157 offset:61056
	ds_read_b128 v[188:191], v157 offset:65408
	s_setprio 1
	s_waitcnt lgkmcnt(7)
	v_mfma_f32_16x16x32_bf16 v[96:99], v[44:47], v[40:43], v[96:99]
	v_mfma_f32_16x16x32_bf16 v[44:47], v[44:47], v[52:55], v[56:59]
	s_waitcnt lgkmcnt(6)
	v_mfma_f32_16x16x32_bf16 v[56:59], v[48:51], v[40:43], v[84:87]
	v_mfma_f32_16x16x32_bf16 v[48:51], v[48:51], v[52:55], v[60:63]
	s_waitcnt lgkmcnt(5)
	v_mfma_f32_16x16x32_bf16 v[60:63], v[138:141], v[40:43], v[100:103]
	v_mfma_f32_16x16x32_bf16 v[64:67], v[138:141], v[52:55], v[64:67]
	s_waitcnt lgkmcnt(4)
	v_mfma_f32_16x16x32_bf16 v[84:87], v[142:145], v[40:43], v[118:121]
	v_mfma_f32_16x16x32_bf16 v[68:71], v[142:145], v[52:55], v[68:71]
	s_waitcnt lgkmcnt(3)
	v_mfma_f32_16x16x32_bf16 v[100:103], v[146:149], v[40:43], v[122:125]
	v_mfma_f32_16x16x32_bf16 v[72:75], v[146:149], v[52:55], v[72:75]
	s_waitcnt lgkmcnt(2)
	v_mfma_f32_16x16x32_bf16 v[118:121], v[150:153], v[40:43], v[130:133]
	v_mfma_f32_16x16x32_bf16 v[76:79], v[150:153], v[52:55], v[76:79]
	s_waitcnt lgkmcnt(1)
	v_mfma_f32_16x16x32_bf16 v[122:125], v[158:161], v[40:43], v[134:137]
	v_mfma_f32_16x16x32_bf16 v[130:133], v[158:161], v[52:55], v[80:83]
	s_waitcnt lgkmcnt(0)
	v_mfma_f32_16x16x32_bf16 v[134:137], v[188:191], v[40:43], v[32:35]
	v_mfma_f32_16x16x32_bf16 v[138:141], v[188:191], v[52:55], v[36:39]
	s_setprio 0
	s_nop 1
	ds_read_b128 v[36:39], v157 offset:35008
	ds_read_b128 v[52:55], v157 offset:39360
	ds_read_b128 v[80:83], v157 offset:43712
	ds_read_b128 v[142:145], v157 offset:48064
	ds_read_b128 v[146:149], v157 offset:52416
	ds_read_b128 v[150:153], v157 offset:56768
	ds_read_b128 v[158:161], v157 offset:61120
	ds_read_b128 v[188:191], v157 offset:65472
	s_setprio 1
	s_waitcnt lgkmcnt(7)
	v_mfma_f32_16x16x32_bf16 v[32:35], v[36:39], v[88:91], v[96:99]
	v_mfma_f32_16x16x32_bf16 v[36:39], v[36:39], v[92:95], v[44:47]
	s_waitcnt lgkmcnt(6)
	v_mfma_f32_16x16x32_bf16 v[40:43], v[52:55], v[88:91], v[56:59]
	v_mfma_f32_16x16x32_bf16 v[44:47], v[52:55], v[92:95], v[48:51]
	s_waitcnt lgkmcnt(5)
	v_mfma_f32_16x16x32_bf16 v[48:51], v[80:83], v[88:91], v[60:63]
	v_mfma_f32_16x16x32_bf16 v[52:55], v[80:83], v[92:95], v[64:67]
	s_waitcnt lgkmcnt(4)
	v_mfma_f32_16x16x32_bf16 v[56:59], v[142:145], v[88:91], v[84:87]
	v_mfma_f32_16x16x32_bf16 v[60:63], v[142:145], v[92:95], v[68:71]
	s_waitcnt lgkmcnt(3)
	v_mfma_f32_16x16x32_bf16 v[64:67], v[146:149], v[88:91], v[100:103]
	v_mfma_f32_16x16x32_bf16 v[68:71], v[146:149], v[92:95], v[72:75]
	s_waitcnt lgkmcnt(2)
	v_mfma_f32_16x16x32_bf16 v[72:75], v[150:153], v[88:91], v[118:121]
	v_mfma_f32_16x16x32_bf16 v[76:79], v[150:153], v[92:95], v[76:79]
	s_waitcnt lgkmcnt(1)
	v_mfma_f32_16x16x32_bf16 v[80:83], v[158:161], v[88:91], v[122:125]
	v_mfma_f32_16x16x32_bf16 v[84:87], v[158:161], v[92:95], v[130:133]
	s_waitcnt lgkmcnt(0)
	v_mfma_f32_16x16x32_bf16 v[88:91], v[188:191], v[88:91], v[134:137]
	v_mfma_f32_16x16x32_bf16 v[92:95], v[188:191], v[92:95], v[138:141]
	s_setprio 0
	s_lshl_b64 s[4:5], s[70:71], 15
	s_add_u32 s4, s80, s4
	s_addc_u32 s5, s81, s5
	v_lshlrev_b64 v[96:97], 8, v[104:105]
	v_lshl_add_u64 v[98:99], s[4:5], 0, v[96:97]
	s_lshl_b64 s[4:5], s[68:69], 15
	s_add_u32 s4, s80, s4
	s_addc_u32 s5, s81, s5
	v_lshl_add_u64 v[100:101], v[98:99], 0, v[128:129]
	v_lshl_add_u64 v[96:97], s[4:5], 0, v[96:97]
	s_barrier
	v_lshl_add_u64 v[102:103], v[96:97], 0, v[128:129]
	global_load_dwordx4 v[204:207], v[100:101], off
	s_movk_i32 s5, 0x2000
	v_add_co_u32_e32 v104, vcc, s5, v100
	s_movk_i32 s2, 0x4000
	s_nop 0
	v_addc_co_u32_e32 v105, vcc, 0, v101, vcc
	s_movk_i32 s4, 0x6000
	s_movk_i32 s6, 0x7000
	v_mov_b64_e32 v[132:133], v[10:11]
	v_mov_b64_e32 v[130:131], v[8:9]
	v_mov_b64_e32 v[136:137], v[6:7]
	v_mov_b64_e32 v[134:135], v[4:5]
	v_mov_b64_e32 v[140:141], v[2:3]
	v_mov_b64_e32 v[138:139], v[0:1]
	global_load_dwordx4 v[208:211], v[104:105], off offset:-4096
	global_load_dwordx4 v[216:219], v[104:105], off
	v_add_co_u32_e32 v104, vcc, s2, v100
	v_addc_co_u32_e32 v105, vcc, 0, v101, vcc
	global_load_dwordx4 v[220:223], v[104:105], off offset:-4096
	global_load_dwordx4 v[224:227], v[104:105], off
	v_add_co_u32_e32 v104, vcc, s4, v100
	v_addc_co_u32_e32 v105, vcc, 0, v101, vcc
	global_load_dwordx4 v[228:231], v[104:105], off offset:-4096
	global_load_dwordx4 v[232:235], v[104:105], off
	v_add_co_u32_e32 v96, vcc, s6, v100
	s_nop 1
	v_addc_co_u32_e32 v97, vcc, 0, v101, vcc
	global_load_dwordx4 v[236:239], v[96:97], off
	s_waitcnt vmcnt(0)
	ds_write_b128 v107, v[204:207]
	ds_write_b128 v107, v[208:211] offset:4352
	ds_write_b128 v107, v[216:219] offset:8704
	ds_write_b128 v107, v[220:223] offset:13056
	ds_write_b128 v107, v[224:227] offset:17408
	ds_write_b128 v107, v[228:231] offset:21760
	ds_write_b128 v107, v[232:235] offset:26112
	ds_write_b128 v107, v[236:239] offset:30464
	v_add_co_u32_e32 v100, vcc, s5, v102
	global_load_dwordx4 v[204:207], v[102:103], off
	v_addc_co_u32_e32 v101, vcc, 0, v103, vcc
	global_load_dwordx4 v[208:211], v[100:101], off offset:-4096
	global_load_dwordx4 v[216:219], v[100:101], off
	v_add_co_u32_e32 v100, vcc, s2, v102
	v_addc_co_u32_e32 v101, vcc, 0, v103, vcc
	global_load_dwordx4 v[220:223], v[100:101], off offset:-4096
	global_load_dwordx4 v[224:227], v[100:101], off
	v_add_co_u32_e32 v100, vcc, s4, v102
	v_addc_co_u32_e32 v101, vcc, 0, v103, vcc
	global_load_dwordx4 v[228:231], v[100:101], off offset:-4096
	global_load_dwordx4 v[232:235], v[100:101], off
	v_add_co_u32_e32 v96, vcc, s6, v102
	s_nop 1
	v_addc_co_u32_e32 v97, vcc, 0, v103, vcc
	global_load_dwordx4 v[236:239], v[96:97], off
	s_waitcnt vmcnt(0)
	ds_write_b128 v107, v[204:207] offset:34816
	ds_write_b128 v107, v[208:211] offset:39168
	ds_write_b128 v107, v[216:219] offset:43520
	ds_write_b128 v107, v[220:223] offset:47872
	ds_write_b128 v107, v[224:227] offset:52224
	ds_write_b128 v107, v[228:231] offset:56576
	ds_write_b128 v107, v[232:235] offset:60928
	ds_write_b128 v107, v[236:239] offset:65280
	v_mov_b64_e32 v[98:99], v[30:31]
	v_mov_b64_e32 v[96:97], v[28:29]
	s_waitcnt lgkmcnt(0)
	s_barrier
	s_nop 0
	v_lshlrev_b32_e32 v100, 16, v96
	v_and_b32_e32 v101, 0xffff0000, v96
	v_pk_mul_f32 v[100:101], v[116:117], v[100:101] op_sel_hi:[0,1]
	v_cvt_pk_bf16_f32 v96, v100, v101
	v_lshlrev_b32_e32 v100, 16, v97
	v_and_b32_e32 v101, 0xffff0000, v97
	v_pk_mul_f32 v[100:101], v[116:117], v[100:101] op_sel_hi:[0,1]
	v_cvt_pk_bf16_f32 v97, v100, v101
	v_lshlrev_b32_e32 v100, 16, v98
	v_and_b32_e32 v101, 0xffff0000, v98
	v_pk_mul_f32 v[100:101], v[116:117], v[100:101] op_sel_hi:[0,1]
	v_cvt_pk_bf16_f32 v98, v100, v101
	v_lshlrev_b32_e32 v100, 16, v99
	v_and_b32_e32 v101, 0xffff0000, v99
	v_pk_mul_f32 v[100:101], v[116:117], v[100:101] op_sel_hi:[0,1]
	v_cvt_pk_bf16_f32 v99, v100, v101
	v_mov_b64_e32 v[102:103], v[26:27]
	v_mov_b64_e32 v[100:101], v[24:25]
	s_nop 0
	v_lshlrev_b32_e32 v104, 16, v100
	v_and_b32_e32 v105, 0xffff0000, v100
	v_pk_mul_f32 v[104:105], v[114:115], v[104:105] op_sel_hi:[0,1]
	v_cvt_pk_bf16_f32 v100, v104, v105
	v_lshlrev_b32_e32 v104, 16, v101
	v_and_b32_e32 v105, 0xffff0000, v101
	v_pk_mul_f32 v[104:105], v[114:115], v[104:105] op_sel_hi:[0,1]
	v_cvt_pk_bf16_f32 v101, v104, v105
	v_lshlrev_b32_e32 v104, 16, v102
	v_and_b32_e32 v105, 0xffff0000, v102
	v_pk_mul_f32 v[104:105], v[114:115], v[104:105] op_sel_hi:[0,1]
	v_cvt_pk_bf16_f32 v102, v104, v105
	v_lshlrev_b32_e32 v104, 16, v103
	v_and_b32_e32 v105, 0xffff0000, v103
	v_pk_mul_f32 v[104:105], v[114:115], v[104:105] op_sel_hi:[0,1]
	v_cvt_pk_bf16_f32 v103, v104, v105
	v_mov_b64_e32 v[106:107], v[22:23]
	v_mov_b64_e32 v[104:105], v[20:21]
	s_nop 0
	v_lshlrev_b32_e32 v118, 16, v104
	v_and_b32_e32 v119, 0xffff0000, v104
	v_pk_mul_f32 v[118:119], v[116:117], v[118:119] op_sel_hi:[0,1]
	v_cvt_pk_bf16_f32 v104, v118, v119
	v_lshlrev_b32_e32 v118, 16, v105
	v_and_b32_e32 v119, 0xffff0000, v105
	v_pk_mul_f32 v[118:119], v[116:117], v[118:119] op_sel_hi:[0,1]
	v_cvt_pk_bf16_f32 v105, v118, v119
	v_lshlrev_b32_e32 v118, 16, v106
	v_and_b32_e32 v119, 0xffff0000, v106
	v_pk_mul_f32 v[118:119], v[116:117], v[118:119] op_sel_hi:[0,1]
	v_cvt_pk_bf16_f32 v106, v118, v119
	v_lshlrev_b32_e32 v118, 16, v107
	v_and_b32_e32 v119, 0xffff0000, v107
	v_pk_mul_f32 v[118:119], v[116:117], v[118:119] op_sel_hi:[0,1]
	v_cvt_pk_bf16_f32 v107, v118, v119
	v_mov_b64_e32 v[120:121], v[18:19]
	v_mov_b64_e32 v[118:119], v[16:17]
	s_nop 0
	v_lshlrev_b32_e32 v122, 16, v118
	v_and_b32_e32 v123, 0xffff0000, v118
	v_pk_mul_f32 v[122:123], v[114:115], v[122:123] op_sel_hi:[0,1]
	v_cvt_pk_bf16_f32 v118, v122, v123
	v_lshlrev_b32_e32 v122, 16, v119
	v_and_b32_e32 v123, 0xffff0000, v119
	v_pk_mul_f32 v[122:123], v[114:115], v[122:123] op_sel_hi:[0,1]
	v_cvt_pk_bf16_f32 v119, v122, v123
	v_lshlrev_b32_e32 v122, 16, v120
	v_and_b32_e32 v123, 0xffff0000, v120
	v_pk_mul_f32 v[122:123], v[114:115], v[122:123] op_sel_hi:[0,1]
	v_cvt_pk_bf16_f32 v120, v122, v123
	v_lshlrev_b32_e32 v122, 16, v121
	v_and_b32_e32 v123, 0xffff0000, v121
	v_pk_mul_f32 v[122:123], v[114:115], v[122:123] op_sel_hi:[0,1]
	v_cvt_pk_bf16_f32 v121, v122, v123
	v_mov_b64_e32 v[124:125], v[14:15]
	v_mov_b64_e32 v[122:123], v[12:13]
	s_nop 0
	v_lshlrev_b32_e32 v126, 16, v122
	v_and_b32_e32 v127, 0xffff0000, v122
	v_pk_mul_f32 v[126:127], v[116:117], v[126:127] op_sel_hi:[0,1]
	v_cvt_pk_bf16_f32 v122, v126, v127
	v_lshlrev_b32_e32 v126, 16, v123
	v_and_b32_e32 v127, 0xffff0000, v123
	v_pk_mul_f32 v[126:127], v[116:117], v[126:127] op_sel_hi:[0,1]
	v_cvt_pk_bf16_f32 v123, v126, v127
	v_lshlrev_b32_e32 v126, 16, v124
	v_and_b32_e32 v127, 0xffff0000, v124
	v_pk_mul_f32 v[126:127], v[116:117], v[126:127] op_sel_hi:[0,1]
	v_cvt_pk_bf16_f32 v124, v126, v127
	v_lshlrev_b32_e32 v126, 16, v125
	v_and_b32_e32 v127, 0xffff0000, v125
	v_pk_mul_f32 v[126:127], v[116:117], v[126:127] op_sel_hi:[0,1]
	v_cvt_pk_bf16_f32 v125, v126, v127
	v_lshlrev_b32_e32 v126, 16, v130
	v_and_b32_e32 v127, 0xffff0000, v130
	v_pk_mul_f32 v[126:127], v[114:115], v[126:127] op_sel_hi:[0,1]
	v_cvt_pk_bf16_f32 v130, v126, v127
	v_lshlrev_b32_e32 v126, 16, v131
	v_and_b32_e32 v127, 0xffff0000, v131
	v_pk_mul_f32 v[126:127], v[114:115], v[126:127] op_sel_hi:[0,1]
	v_cvt_pk_bf16_f32 v131, v126, v127
	v_lshlrev_b32_e32 v126, 16, v132
	v_and_b32_e32 v127, 0xffff0000, v132
	v_pk_mul_f32 v[126:127], v[114:115], v[126:127] op_sel_hi:[0,1]
	v_cvt_pk_bf16_f32 v132, v126, v127
	v_lshlrev_b32_e32 v126, 16, v133
	v_and_b32_e32 v127, 0xffff0000, v133
	v_pk_mul_f32 v[126:127], v[114:115], v[126:127] op_sel_hi:[0,1]
	v_cvt_pk_bf16_f32 v133, v126, v127
	v_lshlrev_b32_e32 v126, 16, v134
	v_and_b32_e32 v127, 0xffff0000, v134
	v_pk_mul_f32 v[126:127], v[116:117], v[126:127] op_sel_hi:[0,1]
	v_cvt_pk_bf16_f32 v134, v126, v127
	v_lshlrev_b32_e32 v126, 16, v135
	v_and_b32_e32 v127, 0xffff0000, v135
	v_pk_mul_f32 v[126:127], v[116:117], v[126:127] op_sel_hi:[0,1]
	v_cvt_pk_bf16_f32 v135, v126, v127
	v_lshlrev_b32_e32 v126, 16, v136
	v_and_b32_e32 v127, 0xffff0000, v136
	v_pk_mul_f32 v[126:127], v[116:117], v[126:127] op_sel_hi:[0,1]
	v_cvt_pk_bf16_f32 v136, v126, v127
	v_lshlrev_b32_e32 v126, 16, v137
	v_and_b32_e32 v127, 0xffff0000, v137
	v_pk_mul_f32 v[116:117], v[116:117], v[126:127] op_sel_hi:[0,1]
	v_cvt_pk_bf16_f32 v137, v116, v117
	v_lshlrev_b32_e32 v116, 16, v138
	v_and_b32_e32 v117, 0xffff0000, v138
	v_pk_mul_f32 v[116:117], v[114:115], v[116:117] op_sel_hi:[0,1]
	v_cvt_pk_bf16_f32 v138, v116, v117
	v_lshlrev_b32_e32 v116, 16, v139
	v_and_b32_e32 v117, 0xffff0000, v139
	v_pk_mul_f32 v[116:117], v[114:115], v[116:117] op_sel_hi:[0,1]
	v_cvt_pk_bf16_f32 v139, v116, v117
	v_lshlrev_b32_e32 v116, 16, v140
	v_and_b32_e32 v117, 0xffff0000, v140
	v_pk_mul_f32 v[116:117], v[114:115], v[116:117] op_sel_hi:[0,1]
	v_cvt_pk_bf16_f32 v140, v116, v117
	v_lshlrev_b32_e32 v116, 16, v141
	v_and_b32_e32 v117, 0xffff0000, v141
	v_pk_mul_f32 v[114:115], v[114:115], v[116:117] op_sel_hi:[0,1]
	v_cvt_pk_bf16_f32 v141, v114, v115
	ds_read_b128 v[114:117], v157
	ds_read_b128 v[142:145], v157 offset:4352
	ds_read_b128 v[146:149], v157 offset:8704
	ds_read_b128 v[150:153], v157 offset:13056
	ds_read_b128 v[158:161], v157 offset:17408
	ds_read_b128 v[188:191], v157 offset:21760
	ds_read_b128 v[192:195], v157 offset:26112
	ds_read_b128 v[196:199], v157 offset:30464
	s_setprio 1
	s_waitcnt lgkmcnt(7)
	v_mfma_f32_16x16x32_bf16 v[32:35], v[114:117], v[96:99], v[32:35]
	v_mfma_f32_16x16x32_bf16 v[36:39], v[114:117], v[100:103], v[36:39]
	s_waitcnt lgkmcnt(6)
	v_mfma_f32_16x16x32_bf16 v[40:43], v[142:145], v[96:99], v[40:43]
	v_mfma_f32_16x16x32_bf16 v[44:47], v[142:145], v[100:103], v[44:47]
	s_waitcnt lgkmcnt(5)
	v_mfma_f32_16x16x32_bf16 v[48:51], v[146:149], v[96:99], v[48:51]
	v_mfma_f32_16x16x32_bf16 v[52:55], v[146:149], v[100:103], v[52:55]
	s_waitcnt lgkmcnt(4)
	v_mfma_f32_16x16x32_bf16 v[56:59], v[150:153], v[96:99], v[56:59]
	v_mfma_f32_16x16x32_bf16 v[60:63], v[150:153], v[100:103], v[60:63]
	s_waitcnt lgkmcnt(3)
	v_mfma_f32_16x16x32_bf16 v[64:67], v[158:161], v[96:99], v[64:67]
	v_mfma_f32_16x16x32_bf16 v[68:71], v[158:161], v[100:103], v[68:71]
	s_waitcnt lgkmcnt(2)
	v_mfma_f32_16x16x32_bf16 v[72:75], v[188:191], v[96:99], v[72:75]
	v_mfma_f32_16x16x32_bf16 v[76:79], v[188:191], v[100:103], v[76:79]
	s_waitcnt lgkmcnt(1)
	v_mfma_f32_16x16x32_bf16 v[80:83], v[192:195], v[96:99], v[80:83]
	v_mfma_f32_16x16x32_bf16 v[84:87], v[192:195], v[100:103], v[84:87]
	s_waitcnt lgkmcnt(0)
	v_mfma_f32_16x16x32_bf16 v[88:91], v[196:199], v[96:99], v[88:91]
	v_mfma_f32_16x16x32_bf16 v[92:95], v[196:199], v[100:103], v[92:95]
	s_setprio 0
	ds_read_b128 v[96:99], v157 offset:64
	ds_read_b128 v[100:103], v157 offset:4416
	ds_read_b128 v[114:117], v157 offset:8768
	ds_read_b128 v[142:145], v157 offset:13120
	ds_read_b128 v[146:149], v157 offset:17472
	ds_read_b128 v[150:153], v157 offset:21824
	ds_read_b128 v[158:161], v157 offset:26176
	ds_read_b128 v[188:191], v157 offset:30528
	s_setprio 1
	s_waitcnt lgkmcnt(7)
	v_mfma_f32_16x16x32_bf16 v[32:35], v[96:99], v[104:107], v[32:35]
	v_mfma_f32_16x16x32_bf16 v[36:39], v[96:99], v[118:121], v[36:39]
	s_waitcnt lgkmcnt(6)
	v_mfma_f32_16x16x32_bf16 v[40:43], v[100:103], v[104:107], v[40:43]
	v_mfma_f32_16x16x32_bf16 v[44:47], v[100:103], v[118:121], v[44:47]
	s_waitcnt lgkmcnt(5)
	v_mfma_f32_16x16x32_bf16 v[48:51], v[114:117], v[104:107], v[48:51]
	v_mfma_f32_16x16x32_bf16 v[52:55], v[114:117], v[118:121], v[52:55]
	s_waitcnt lgkmcnt(4)
	v_mfma_f32_16x16x32_bf16 v[56:59], v[142:145], v[104:107], v[56:59]
	v_mfma_f32_16x16x32_bf16 v[60:63], v[142:145], v[118:121], v[60:63]
	s_waitcnt lgkmcnt(3)
	v_mfma_f32_16x16x32_bf16 v[64:67], v[146:149], v[104:107], v[64:67]
	v_mfma_f32_16x16x32_bf16 v[68:71], v[146:149], v[118:121], v[68:71]
	s_waitcnt lgkmcnt(2)
	v_mfma_f32_16x16x32_bf16 v[72:75], v[150:153], v[104:107], v[72:75]
	v_mfma_f32_16x16x32_bf16 v[76:79], v[150:153], v[118:121], v[76:79]
	s_waitcnt lgkmcnt(1)
	v_mfma_f32_16x16x32_bf16 v[80:83], v[158:161], v[104:107], v[80:83]
	v_mfma_f32_16x16x32_bf16 v[84:87], v[158:161], v[118:121], v[84:87]
	s_waitcnt lgkmcnt(0)
	v_mfma_f32_16x16x32_bf16 v[88:91], v[188:191], v[104:107], v[88:91]
	v_mfma_f32_16x16x32_bf16 v[92:95], v[188:191], v[118:121], v[92:95]
	s_setprio 0
	ds_read_b128 v[96:99], v157 offset:128
	ds_read_b128 v[100:103], v157 offset:4480
	ds_read_b128 v[104:107], v157 offset:8832
	ds_read_b128 v[114:117], v157 offset:13184
	ds_read_b128 v[118:121], v157 offset:17536
	ds_read_b128 v[142:145], v157 offset:21888
	ds_read_b128 v[146:149], v157 offset:26240
	ds_read_b128 v[150:153], v157 offset:30592
	s_setprio 1
	s_waitcnt lgkmcnt(7)
	v_mfma_f32_16x16x32_bf16 v[32:35], v[96:99], v[122:125], v[32:35]
	v_mfma_f32_16x16x32_bf16 v[36:39], v[96:99], v[130:133], v[36:39]
	s_waitcnt lgkmcnt(6)
	v_mfma_f32_16x16x32_bf16 v[40:43], v[100:103], v[122:125], v[40:43]
	v_mfma_f32_16x16x32_bf16 v[44:47], v[100:103], v[130:133], v[44:47]
	s_waitcnt lgkmcnt(5)
	v_mfma_f32_16x16x32_bf16 v[48:51], v[104:107], v[122:125], v[48:51]
	v_mfma_f32_16x16x32_bf16 v[52:55], v[104:107], v[130:133], v[52:55]
	s_waitcnt lgkmcnt(4)
	v_mfma_f32_16x16x32_bf16 v[56:59], v[114:117], v[122:125], v[56:59]
	v_mfma_f32_16x16x32_bf16 v[60:63], v[114:117], v[130:133], v[60:63]
	s_waitcnt lgkmcnt(3)
	v_mfma_f32_16x16x32_bf16 v[64:67], v[118:121], v[122:125], v[64:67]
	v_mfma_f32_16x16x32_bf16 v[68:71], v[118:121], v[130:133], v[68:71]
	s_waitcnt lgkmcnt(2)
	v_mfma_f32_16x16x32_bf16 v[72:75], v[142:145], v[122:125], v[72:75]
	v_mfma_f32_16x16x32_bf16 v[76:79], v[142:145], v[130:133], v[76:79]
	s_waitcnt lgkmcnt(1)
	v_mfma_f32_16x16x32_bf16 v[80:83], v[146:149], v[122:125], v[80:83]
	v_mfma_f32_16x16x32_bf16 v[84:87], v[146:149], v[130:133], v[84:87]
	s_waitcnt lgkmcnt(0)
	v_mfma_f32_16x16x32_bf16 v[88:91], v[150:153], v[122:125], v[88:91]
	v_mfma_f32_16x16x32_bf16 v[92:95], v[150:153], v[130:133], v[92:95]
	s_setprio 0
	ds_read_b128 v[96:99], v157 offset:192
	ds_read_b128 v[100:103], v157 offset:4544
	ds_read_b128 v[104:107], v157 offset:8896
	ds_read_b128 v[114:117], v157 offset:13248
	ds_read_b128 v[118:121], v157 offset:17600
	ds_read_b128 v[122:125], v157 offset:21952
	ds_read_b128 v[130:133], v157 offset:26304
	ds_read_b128 v[142:145], v157 offset:30656
	s_setprio 1
	s_waitcnt lgkmcnt(7)
	v_mfma_f32_16x16x32_bf16 v[32:35], v[96:99], v[134:137], v[32:35]
	v_mfma_f32_16x16x32_bf16 v[36:39], v[96:99], v[138:141], v[36:39]
	s_waitcnt lgkmcnt(6)
	v_mfma_f32_16x16x32_bf16 v[40:43], v[100:103], v[134:137], v[40:43]
	v_mfma_f32_16x16x32_bf16 v[44:47], v[100:103], v[138:141], v[44:47]
	s_waitcnt lgkmcnt(5)
	v_mfma_f32_16x16x32_bf16 v[48:51], v[104:107], v[134:137], v[48:51]
	v_mfma_f32_16x16x32_bf16 v[52:55], v[104:107], v[138:141], v[52:55]
	s_waitcnt lgkmcnt(4)
	v_mfma_f32_16x16x32_bf16 v[56:59], v[114:117], v[134:137], v[56:59]
	v_mfma_f32_16x16x32_bf16 v[60:63], v[114:117], v[138:141], v[60:63]
	s_waitcnt lgkmcnt(3)
	v_mfma_f32_16x16x32_bf16 v[64:67], v[118:121], v[134:137], v[64:67]
	v_mfma_f32_16x16x32_bf16 v[68:71], v[118:121], v[138:141], v[68:71]
	s_waitcnt lgkmcnt(2)
	v_mfma_f32_16x16x32_bf16 v[72:75], v[122:125], v[134:137], v[72:75]
	v_mfma_f32_16x16x32_bf16 v[76:79], v[122:125], v[138:141], v[76:79]
	s_waitcnt lgkmcnt(1)
	v_mfma_f32_16x16x32_bf16 v[80:83], v[130:133], v[134:137], v[80:83]
	v_mfma_f32_16x16x32_bf16 v[84:87], v[130:133], v[138:141], v[84:87]
	s_waitcnt lgkmcnt(0)
	v_mfma_f32_16x16x32_bf16 v[88:91], v[142:145], v[134:137], v[88:91]
	v_mfma_f32_16x16x32_bf16 v[92:95], v[142:145], v[138:141], v[92:95]
	s_setprio 0
	s_nop 0
	v_lshlrev_b32_e32 v96, 16, v28
	v_and_b32_e32 v97, 0xffff0000, v28
	v_pk_mul_f32 v[96:97], v[112:113], v[96:97] op_sel_hi:[0,1]
	v_cvt_pk_bf16_f32 v28, v96, v97
	v_lshlrev_b32_e32 v96, 16, v29
	v_and_b32_e32 v97, 0xffff0000, v29
	v_pk_mul_f32 v[96:97], v[112:113], v[96:97] op_sel_hi:[0,1]
	v_cvt_pk_bf16_f32 v29, v96, v97
	v_lshlrev_b32_e32 v96, 16, v30
	v_and_b32_e32 v97, 0xffff0000, v30
	v_pk_mul_f32 v[96:97], v[112:113], v[96:97] op_sel_hi:[0,1]
	v_cvt_pk_bf16_f32 v30, v96, v97
	v_lshlrev_b32_e32 v96, 16, v31
	v_and_b32_e32 v97, 0xffff0000, v31
	v_pk_mul_f32 v[96:97], v[112:113], v[96:97] op_sel_hi:[0,1]
	v_cvt_pk_bf16_f32 v31, v96, v97
	v_lshlrev_b32_e32 v96, 16, v24
	v_and_b32_e32 v97, 0xffff0000, v24
	v_pk_mul_f32 v[96:97], v[110:111], v[96:97] op_sel_hi:[0,1]
	v_cvt_pk_bf16_f32 v24, v96, v97
	v_lshlrev_b32_e32 v96, 16, v25
	v_and_b32_e32 v97, 0xffff0000, v25
	v_pk_mul_f32 v[96:97], v[110:111], v[96:97] op_sel_hi:[0,1]
	v_cvt_pk_bf16_f32 v25, v96, v97
	v_lshlrev_b32_e32 v96, 16, v26
	v_and_b32_e32 v97, 0xffff0000, v26
	v_pk_mul_f32 v[96:97], v[110:111], v[96:97] op_sel_hi:[0,1]
	v_cvt_pk_bf16_f32 v26, v96, v97
	v_lshlrev_b32_e32 v96, 16, v27
	v_and_b32_e32 v97, 0xffff0000, v27
	v_pk_mul_f32 v[96:97], v[110:111], v[96:97] op_sel_hi:[0,1]
	v_cvt_pk_bf16_f32 v27, v96, v97
	v_lshlrev_b32_e32 v96, 16, v20
	v_and_b32_e32 v97, 0xffff0000, v20
	v_pk_mul_f32 v[96:97], v[112:113], v[96:97] op_sel_hi:[0,1]
	v_cvt_pk_bf16_f32 v20, v96, v97
	v_lshlrev_b32_e32 v96, 16, v21
	v_and_b32_e32 v97, 0xffff0000, v21
	v_pk_mul_f32 v[96:97], v[112:113], v[96:97] op_sel_hi:[0,1]
	v_cvt_pk_bf16_f32 v21, v96, v97
	v_lshlrev_b32_e32 v96, 16, v22
	v_and_b32_e32 v97, 0xffff0000, v22
	v_pk_mul_f32 v[96:97], v[112:113], v[96:97] op_sel_hi:[0,1]
	v_cvt_pk_bf16_f32 v22, v96, v97
	v_lshlrev_b32_e32 v96, 16, v23
	v_and_b32_e32 v97, 0xffff0000, v23
	v_pk_mul_f32 v[96:97], v[112:113], v[96:97] op_sel_hi:[0,1]
	v_cvt_pk_bf16_f32 v23, v96, v97
	v_lshlrev_b32_e32 v96, 16, v16
	v_and_b32_e32 v97, 0xffff0000, v16
	v_pk_mul_f32 v[96:97], v[110:111], v[96:97] op_sel_hi:[0,1]
	v_cvt_pk_bf16_f32 v16, v96, v97
	v_lshlrev_b32_e32 v96, 16, v17
	v_and_b32_e32 v97, 0xffff0000, v17
	v_pk_mul_f32 v[96:97], v[110:111], v[96:97] op_sel_hi:[0,1]
	v_cvt_pk_bf16_f32 v17, v96, v97
	v_lshlrev_b32_e32 v96, 16, v18
	v_and_b32_e32 v97, 0xffff0000, v18
	v_pk_mul_f32 v[96:97], v[110:111], v[96:97] op_sel_hi:[0,1]
	v_cvt_pk_bf16_f32 v18, v96, v97
	v_lshlrev_b32_e32 v96, 16, v19
	v_and_b32_e32 v97, 0xffff0000, v19
	v_pk_mul_f32 v[96:97], v[110:111], v[96:97] op_sel_hi:[0,1]
	v_cvt_pk_bf16_f32 v19, v96, v97
	v_lshlrev_b32_e32 v96, 16, v12
	v_and_b32_e32 v97, 0xffff0000, v12
	v_pk_mul_f32 v[96:97], v[112:113], v[96:97] op_sel_hi:[0,1]
	v_cvt_pk_bf16_f32 v12, v96, v97
	v_lshlrev_b32_e32 v96, 16, v13
	v_and_b32_e32 v97, 0xffff0000, v13
	v_pk_mul_f32 v[96:97], v[112:113], v[96:97] op_sel_hi:[0,1]
	v_cvt_pk_bf16_f32 v13, v96, v97
	v_lshlrev_b32_e32 v96, 16, v14
	v_and_b32_e32 v97, 0xffff0000, v14
	v_pk_mul_f32 v[96:97], v[112:113], v[96:97] op_sel_hi:[0,1]
	v_cvt_pk_bf16_f32 v14, v96, v97
	v_lshlrev_b32_e32 v96, 16, v15
	v_and_b32_e32 v97, 0xffff0000, v15
	v_pk_mul_f32 v[96:97], v[112:113], v[96:97] op_sel_hi:[0,1]
	v_cvt_pk_bf16_f32 v15, v96, v97
	v_lshlrev_b32_e32 v96, 16, v8
	v_and_b32_e32 v97, 0xffff0000, v8
	v_pk_mul_f32 v[96:97], v[110:111], v[96:97] op_sel_hi:[0,1]
	v_cvt_pk_bf16_f32 v8, v96, v97
	v_lshlrev_b32_e32 v96, 16, v9
	v_and_b32_e32 v97, 0xffff0000, v9
	v_pk_mul_f32 v[96:97], v[110:111], v[96:97] op_sel_hi:[0,1]
	v_cvt_pk_bf16_f32 v9, v96, v97
	v_lshlrev_b32_e32 v96, 16, v10
	v_and_b32_e32 v97, 0xffff0000, v10
	v_pk_mul_f32 v[96:97], v[110:111], v[96:97] op_sel_hi:[0,1]
	v_cvt_pk_bf16_f32 v10, v96, v97
	v_lshlrev_b32_e32 v96, 16, v11
	v_and_b32_e32 v97, 0xffff0000, v11
	v_pk_mul_f32 v[96:97], v[110:111], v[96:97] op_sel_hi:[0,1]
	v_cvt_pk_bf16_f32 v11, v96, v97
	v_lshlrev_b32_e32 v96, 16, v4
	v_and_b32_e32 v97, 0xffff0000, v4
	v_lshlrev_b32_e32 v4, 16, v5
	v_and_b32_e32 v5, 0xffff0000, v5
	v_pk_mul_f32 v[96:97], v[112:113], v[96:97] op_sel_hi:[0,1]
	v_pk_mul_f32 v[4:5], v[112:113], v[4:5] op_sel_hi:[0,1]
	v_cvt_pk_bf16_f32 v96, v96, v97
	v_cvt_pk_bf16_f32 v97, v4, v5
	v_lshlrev_b32_e32 v4, 16, v6
	v_and_b32_e32 v5, 0xffff0000, v6
	v_pk_mul_f32 v[4:5], v[112:113], v[4:5] op_sel_hi:[0,1]
	v_cvt_pk_bf16_f32 v98, v4, v5
	v_lshlrev_b32_e32 v4, 16, v7
	v_and_b32_e32 v5, 0xffff0000, v7
	v_pk_mul_f32 v[4:5], v[112:113], v[4:5] op_sel_hi:[0,1]
	v_cvt_pk_bf16_f32 v99, v4, v5
	s_nop 0
	v_lshlrev_b32_e32 v4, 16, v0
	v_and_b32_e32 v5, 0xffff0000, v0
	v_pk_mul_f32 v[4:5], v[110:111], v[4:5] op_sel_hi:[0,1]
	v_cvt_pk_bf16_f32 v0, v4, v5
	v_lshlrev_b32_e32 v4, 16, v1
	v_and_b32_e32 v5, 0xffff0000, v1
	v_pk_mul_f32 v[4:5], v[110:111], v[4:5] op_sel_hi:[0,1]
	v_cvt_pk_bf16_f32 v1, v4, v5
	v_lshlrev_b32_e32 v4, 16, v2
	v_and_b32_e32 v5, 0xffff0000, v2
	v_pk_mul_f32 v[4:5], v[110:111], v[4:5] op_sel_hi:[0,1]
	v_cvt_pk_bf16_f32 v2, v4, v5
	v_lshlrev_b32_e32 v4, 16, v3
	v_and_b32_e32 v5, 0xffff0000, v3
	v_pk_mul_f32 v[4:5], v[110:111], v[4:5] op_sel_hi:[0,1]
	v_cvt_pk_bf16_f32 v3, v4, v5
	ds_read_b128 v[4:7], v157 offset:34816
	ds_read_b128 v[100:103], v157 offset:39168
	ds_read_b128 v[104:107], v157 offset:43520
	ds_read_b128 v[110:113], v157 offset:47872
	ds_read_b128 v[114:117], v157 offset:52224
	ds_read_b128 v[118:121], v157 offset:56576
	ds_read_b128 v[122:125], v157 offset:60928
	ds_read_b128 v[130:133], v157 offset:65280
	s_setprio 1
	s_waitcnt lgkmcnt(7)
	v_mfma_f32_16x16x32_bf16 v[32:35], v[4:7], v[28:31], v[32:35]
	v_mfma_f32_16x16x32_bf16 v[4:7], v[4:7], v[24:27], v[36:39]
	s_waitcnt lgkmcnt(6)
	v_mfma_f32_16x16x32_bf16 v[36:39], v[100:103], v[28:31], v[40:43]
	v_mfma_f32_16x16x32_bf16 v[40:43], v[100:103], v[24:27], v[44:47]
	s_waitcnt lgkmcnt(5)
	v_mfma_f32_16x16x32_bf16 v[44:47], v[104:107], v[28:31], v[48:51]
	v_mfma_f32_16x16x32_bf16 v[48:51], v[104:107], v[24:27], v[52:55]
	s_waitcnt lgkmcnt(4)
	v_mfma_f32_16x16x32_bf16 v[52:55], v[110:113], v[28:31], v[56:59]
	v_mfma_f32_16x16x32_bf16 v[56:59], v[110:113], v[24:27], v[60:63]
	s_waitcnt lgkmcnt(3)
	v_mfma_f32_16x16x32_bf16 v[60:63], v[114:117], v[28:31], v[64:67]
	v_mfma_f32_16x16x32_bf16 v[64:67], v[114:117], v[24:27], v[68:71]
	s_waitcnt lgkmcnt(2)
	v_mfma_f32_16x16x32_bf16 v[68:71], v[118:121], v[28:31], v[72:75]
	v_mfma_f32_16x16x32_bf16 v[72:75], v[118:121], v[24:27], v[76:79]
	s_waitcnt lgkmcnt(1)
	v_mfma_f32_16x16x32_bf16 v[76:79], v[122:125], v[28:31], v[80:83]
	v_mfma_f32_16x16x32_bf16 v[80:83], v[122:125], v[24:27], v[84:87]
	s_waitcnt lgkmcnt(0)
	v_mfma_f32_16x16x32_bf16 v[28:31], v[130:133], v[28:31], v[88:91]
	v_mfma_f32_16x16x32_bf16 v[24:27], v[130:133], v[24:27], v[92:95]
	s_setprio 0
	ds_read_b128 v[84:87], v157 offset:34880
	ds_read_b128 v[88:91], v157 offset:39232
	ds_read_b128 v[92:95], v157 offset:43584
	ds_read_b128 v[100:103], v157 offset:47936
	ds_read_b128 v[104:107], v157 offset:52288
	ds_read_b128 v[110:113], v157 offset:56640
	ds_read_b128 v[114:117], v157 offset:60992
	ds_read_b128 v[118:121], v157 offset:65344
	s_setprio 1
	s_waitcnt lgkmcnt(7)
	v_mfma_f32_16x16x32_bf16 v[32:35], v[84:87], v[20:23], v[32:35]
	v_mfma_f32_16x16x32_bf16 v[4:7], v[84:87], v[16:19], v[4:7]
	s_waitcnt lgkmcnt(6)
	v_mfma_f32_16x16x32_bf16 v[36:39], v[88:91], v[20:23], v[36:39]
	v_mfma_f32_16x16x32_bf16 v[40:43], v[88:91], v[16:19], v[40:43]
	s_waitcnt lgkmcnt(5)
	v_mfma_f32_16x16x32_bf16 v[44:47], v[92:95], v[20:23], v[44:47]
	v_mfma_f32_16x16x32_bf16 v[48:51], v[92:95], v[16:19], v[48:51]
	s_waitcnt lgkmcnt(4)
	v_mfma_f32_16x16x32_bf16 v[52:55], v[100:103], v[20:23], v[52:55]
	v_mfma_f32_16x16x32_bf16 v[56:59], v[100:103], v[16:19], v[56:59]
	s_waitcnt lgkmcnt(3)
	v_mfma_f32_16x16x32_bf16 v[60:63], v[104:107], v[20:23], v[60:63]
	v_mfma_f32_16x16x32_bf16 v[64:67], v[104:107], v[16:19], v[64:67]
	s_waitcnt lgkmcnt(2)
	v_mfma_f32_16x16x32_bf16 v[68:71], v[110:113], v[20:23], v[68:71]
	v_mfma_f32_16x16x32_bf16 v[72:75], v[110:113], v[16:19], v[72:75]
	s_waitcnt lgkmcnt(1)
	v_mfma_f32_16x16x32_bf16 v[76:79], v[114:117], v[20:23], v[76:79]
	v_mfma_f32_16x16x32_bf16 v[80:83], v[114:117], v[16:19], v[80:83]
	s_waitcnt lgkmcnt(0)
	v_mfma_f32_16x16x32_bf16 v[20:23], v[118:121], v[20:23], v[28:31]
	v_mfma_f32_16x16x32_bf16 v[16:19], v[118:121], v[16:19], v[24:27]
	s_setprio 0
	s_nop 1
	ds_read_b128 v[24:27], v157 offset:34944
	ds_read_b128 v[28:31], v157 offset:39296
	ds_read_b128 v[84:87], v157 offset:43648
	ds_read_b128 v[88:91], v157 offset:48000
	ds_read_b128 v[92:95], v157 offset:52352
	ds_read_b128 v[100:103], v157 offset:56704
	ds_read_b128 v[104:107], v157 offset:61056
	ds_read_b128 v[110:113], v157 offset:65408
	s_setprio 1
	s_waitcnt lgkmcnt(7)
	v_mfma_f32_16x16x32_bf16 v[32:35], v[24:27], v[12:15], v[32:35]
	v_mfma_f32_16x16x32_bf16 v[4:7], v[24:27], v[8:11], v[4:7]
	s_waitcnt lgkmcnt(6)
	v_mfma_f32_16x16x32_bf16 v[24:27], v[28:31], v[12:15], v[36:39]
	v_mfma_f32_16x16x32_bf16 v[36:39], v[28:31], v[8:11], v[40:43]
	s_waitcnt lgkmcnt(5)
	v_mfma_f32_16x16x32_bf16 v[40:43], v[84:87], v[12:15], v[44:47]
	v_mfma_f32_16x16x32_bf16 v[44:47], v[84:87], v[8:11], v[48:51]
	s_waitcnt lgkmcnt(4)
	v_mfma_f32_16x16x32_bf16 v[48:51], v[88:91], v[12:15], v[52:55]
	v_mfma_f32_16x16x32_bf16 v[84:87], v[88:91], v[8:11], v[56:59]
	s_waitcnt lgkmcnt(3)
	v_mfma_f32_16x16x32_bf16 v[88:91], v[92:95], v[12:15], v[60:63]
	v_mfma_f32_16x16x32_bf16 v[64:67], v[92:95], v[8:11], v[64:67]
	s_waitcnt lgkmcnt(2)
	v_mfma_f32_16x16x32_bf16 v[68:71], v[100:103], v[12:15], v[68:71]
	v_mfma_f32_16x16x32_bf16 v[72:75], v[100:103], v[8:11], v[72:75]
	s_waitcnt lgkmcnt(1)
	v_mfma_f32_16x16x32_bf16 v[76:79], v[104:107], v[12:15], v[76:79]
	v_mfma_f32_16x16x32_bf16 v[80:83], v[104:107], v[8:11], v[80:83]
	s_waitcnt lgkmcnt(0)
	v_mfma_f32_16x16x32_bf16 v[92:95], v[110:113], v[12:15], v[20:23]
	v_mfma_f32_16x16x32_bf16 v[100:103], v[110:113], v[8:11], v[16:19]
	s_setprio 0
	ds_read_b128 v[8:11], v157 offset:35008
	ds_read_b128 v[12:15], v157 offset:39360
	ds_read_b128 v[16:19], v157 offset:43712
	ds_read_b128 v[104:107], v157 offset:48064
	ds_read_b128 v[110:113], v157 offset:52416
	ds_read_b128 v[114:117], v157 offset:56768
	ds_read_b128 v[118:121], v157 offset:61120
	ds_read_b128 v[122:125], v157 offset:65472
	s_setprio 1
	s_waitcnt lgkmcnt(7)
	v_mfma_f32_16x16x32_bf16 v[60:63], v[8:11], v[96:99], v[32:35]
	v_mfma_f32_16x16x32_bf16 v[28:31], v[8:11], v[0:3], v[4:7]
	s_waitcnt lgkmcnt(6)
	v_mfma_f32_16x16x32_bf16 v[56:59], v[12:15], v[96:99], v[24:27]
	v_mfma_f32_16x16x32_bf16 v[24:27], v[12:15], v[0:3], v[36:39]
	s_waitcnt lgkmcnt(5)
	v_mfma_f32_16x16x32_bf16 v[52:55], v[16:19], v[96:99], v[40:43]
	v_mfma_f32_16x16x32_bf16 v[20:23], v[16:19], v[0:3], v[44:47]
	s_waitcnt lgkmcnt(4)
	v_mfma_f32_16x16x32_bf16 v[48:51], v[104:107], v[96:99], v[48:51]
	v_mfma_f32_16x16x32_bf16 v[16:19], v[104:107], v[0:3], v[84:87]
	s_waitcnt lgkmcnt(3)
	v_mfma_f32_16x16x32_bf16 v[44:47], v[110:113], v[96:99], v[88:91]
	v_mfma_f32_16x16x32_bf16 v[12:15], v[110:113], v[0:3], v[64:67]
	s_waitcnt lgkmcnt(2)
	v_mfma_f32_16x16x32_bf16 v[40:43], v[114:117], v[96:99], v[68:71]
	v_mfma_f32_16x16x32_bf16 v[8:11], v[114:117], v[0:3], v[72:75]
	s_waitcnt lgkmcnt(1)
	v_mfma_f32_16x16x32_bf16 v[36:39], v[118:121], v[96:99], v[76:79]
	v_mfma_f32_16x16x32_bf16 v[4:7], v[118:121], v[0:3], v[80:83]
	s_waitcnt lgkmcnt(0)
	v_mfma_f32_16x16x32_bf16 v[32:35], v[122:125], v[96:99], v[92:95]
	v_mfma_f32_16x16x32_bf16 v[0:3], v[122:125], v[0:3], v[100:103]
	s_setprio 0
	v_mov_b32_e32 v64, v60
	v_mov_b32_e32 v65, v56
	v_mov_b32_e32 v66, v61
	v_mov_b32_e32 v67, v57
	v_pk_add_f32 v[64:65], v[64:65], v[66:67]
	v_mov_b32_e32 v66, v62
	v_mov_b32_e32 v67, v58
	v_pk_add_f32 v[64:65], v[66:67], v[64:65]
	v_mov_b32_e32 v66, v63
	v_mov_b32_e32 v67, v59
	v_pk_add_f32 v[64:65], v[66:67], v[64:65]
	v_mov_b32_e32 v66, v53
	v_add_f32_e32 v64, 0, v64
	v_add_f32_e32 v68, v64, v65
	v_mov_b32_e32 v64, v52
	v_mov_b32_e32 v65, v48
	v_mov_b32_e32 v67, v49
	v_pk_add_f32 v[64:65], v[64:65], v[66:67]
	v_mov_b32_e32 v66, v54
	v_mov_b32_e32 v67, v50
	v_pk_add_f32 v[64:65], v[66:67], v[64:65]
	v_mov_b32_e32 v66, v55
	v_mov_b32_e32 v67, v51
	v_pk_add_f32 v[64:65], v[66:67], v[64:65]
	v_mov_b32_e32 v66, v45
	v_add_f32_e32 v64, v68, v64
	v_add_f32_e32 v68, v64, v65
	v_mov_b32_e32 v64, v44
	v_mov_b32_e32 v65, v40
	v_mov_b32_e32 v67, v41
	v_pk_add_f32 v[64:65], v[64:65], v[66:67]
	v_mov_b32_e32 v66, v46
	v_mov_b32_e32 v67, v42
	v_pk_add_f32 v[64:65], v[66:67], v[64:65]
	v_mov_b32_e32 v66, v47
	v_mov_b32_e32 v67, v43
	v_pk_add_f32 v[64:65], v[66:67], v[64:65]
	v_mov_b32_e32 v66, v37
	v_add_f32_e32 v64, v68, v64
	v_add_f32_e32 v68, v64, v65
	v_mov_b32_e32 v64, v36
	v_mov_b32_e32 v65, v32
	v_mov_b32_e32 v67, v33
	v_pk_add_f32 v[64:65], v[64:65], v[66:67]
	v_mov_b32_e32 v66, v38
	v_mov_b32_e32 v67, v34
	v_pk_add_f32 v[64:65], v[66:67], v[64:65]
	v_mov_b32_e32 v66, v39
	v_mov_b32_e32 v67, v35
	v_pk_add_f32 v[64:65], v[66:67], v[64:65]
	s_load_dwordx16 s[40:55], s[0:1], 0x100
	v_add_f32_e32 v64, v68, v64
	v_add_f32_e32 v64, v64, v65
	ds_bpermute_b32 v65, v109, v64
	s_lshl_b32 s2, s57, 2
	v_readlane_b32 s4, v241, 38
	s_add_u32 s30, s4, s2
	v_readlane_b32 s2, v241, 39
	s_waitcnt lgkmcnt(0)
	v_add_f32_e32 v65, v64, v65
	ds_bpermute_b32 v66, v154, v65
	v_add_u32_e32 v64, s66, v108
	s_addc_u32 s31, s2, 0
	s_lshl_b32 s96, s57, 1
	v_lshlrev_b32_e32 v128, 1, v156
	s_waitcnt lgkmcnt(0)
	v_add_f32_e32 v69, v65, v66
	v_ashrrev_i32_e32 v65, 31, v64
	v_lshlrev_b64 v[66:67], 14, v[64:65]
	v_lshl_add_u64 v[66:67], s[52:53], 0, v[66:67]
	v_lshl_add_u64 v[66:67], v[66:67], 0, s[96:97]
	v_lshl_add_u64 v[78:79], v[66:67], 0, v[128:129]
	s_movk_i32 s38, 0x1000
	v_add_co_u32_e32 v66, vcc, s38, v78
	v_lshlrev_b32_e32 v68, 2, v156
	s_nop 0
	v_addc_co_u32_e32 v67, vcc, 0, v79, vcc
	global_load_dwordx2 v[80:81], v[66:67], off offset:2048
	global_load_dwordx4 v[70:73], v68, s[30:31]
	v_fmamk_f32 v77, v69, 0xbc000000, v61
	v_fmamk_f32 v76, v69, 0xbc000000, v60
	v_mul_f32_e32 v75, v77, v77
	v_fmac_f32_e32 v75, v76, v76
	v_fmamk_f32 v62, v69, 0xbc000000, v62
	v_fmac_f32_e32 v75, v62, v62
	v_fmac_f32_e32 v63, 0xbc000000, v69
	v_fmac_f32_e32 v75, v63, v63
	v_fmamk_f32 v60, v69, 0xbc000000, v56
	v_fmac_f32_e32 v75, v60, v60
	v_fmamk_f32 v61, v69, 0xbc000000, v57
	v_fmac_f32_e32 v75, v61, v61
	v_fmamk_f32 v58, v69, 0xbc000000, v58
	v_fmac_f32_e32 v75, v58, v58
	v_fmac_f32_e32 v59, 0xbc000000, v69
	v_fmac_f32_e32 v75, v59, v59
	v_fmamk_f32 v82, v69, 0xbc000000, v52
	v_fmac_f32_e32 v75, v82, v82
	v_fmamk_f32 v83, v69, 0xbc000000, v53
	v_fmac_f32_e32 v75, v83, v83
	v_fmamk_f32 v54, v69, 0xbc000000, v54
	v_fmac_f32_e32 v75, v54, v54
	v_fmac_f32_e32 v55, 0xbc000000, v69
	v_fmac_f32_e32 v75, v55, v55
	v_fmamk_f32 v66, v69, 0xbc000000, v48
	v_fmac_f32_e32 v75, v66, v66
	v_fmamk_f32 v67, v69, 0xbc000000, v49
	v_fmac_f32_e32 v75, v67, v67
	v_fmamk_f32 v50, v69, 0xbc000000, v50
	v_fmac_f32_e32 v75, v50, v50
	v_fmac_f32_e32 v51, 0xbc000000, v69
	v_fmac_f32_e32 v75, v51, v51
	v_fmamk_f32 v56, v69, 0xbc000000, v44
	v_fmac_f32_e32 v75, v56, v56
	v_fmamk_f32 v57, v69, 0xbc000000, v45
	v_fmac_f32_e32 v75, v57, v57
	v_fmamk_f32 v46, v69, 0xbc000000, v46
	v_fmac_f32_e32 v75, v46, v46
	v_fmac_f32_e32 v47, 0xbc000000, v69
	v_fmac_f32_e32 v75, v47, v47
	v_fmamk_f32 v52, v69, 0xbc000000, v40
	v_fmac_f32_e32 v75, v52, v52
	v_fmamk_f32 v53, v69, 0xbc000000, v41
	v_fmac_f32_e32 v75, v53, v53
	v_fmamk_f32 v42, v69, 0xbc000000, v42
	v_fmac_f32_e32 v75, v42, v42
	v_fmac_f32_e32 v43, 0xbc000000, v69
	v_mul_f32_e32 v74, 0x3c000000, v69
	v_fmac_f32_e32 v75, v43, v43
	v_pk_add_f32 v[40:41], v[36:37], v[74:75] op_sel_hi:[1,0] neg_lo:[0,1] neg_hi:[0,1]
	s_mov_b32 s2, 0x800000
	v_pk_mul_f32 v[40:41], v[40:41], v[40:41]
	s_load_dwordx16 s[4:19], s[0:1], 0x140
	v_add_f32_e32 v40, v40, v75
	v_add_f32_e32 v44, v41, v40
	v_pk_add_f32 v[40:41], v[38:39], v[74:75] op_sel_hi:[1,0] neg_lo:[0,1] neg_hi:[0,1]
	s_mov_b64 s[40:41], 0x1800
	v_pk_mul_f32 v[40:41], v[40:41], v[40:41]
	v_fmamk_f32 v37, v69, 0xbc000000, v37
	v_add_f32_e32 v40, v40, v44
	v_add_f32_e32 v44, v41, v40
	v_pk_add_f32 v[40:41], v[32:33], v[74:75] op_sel_hi:[1,0] neg_lo:[0,1] neg_hi:[0,1]
	v_fmamk_f32 v36, v69, 0xbc000000, v36
	v_pk_mul_f32 v[40:41], v[40:41], v[40:41]
	v_fmamk_f32 v39, v69, 0xbc000000, v39
	v_add_f32_e32 v40, v40, v44
	v_add_f32_e32 v44, v41, v40
	v_pk_add_f32 v[40:41], v[34:35], v[74:75] op_sel_hi:[1,0] neg_lo:[0,1] neg_hi:[0,1]
	v_fmac_f32_e32 v38, 0xbc000000, v69
	v_pk_mul_f32 v[40:41], v[40:41], v[40:41]
	v_fmamk_f32 v33, v69, 0xbc000000, v33
	v_add_f32_e32 v40, v40, v44
	v_add_f32_e32 v40, v41, v40
	ds_bpermute_b32 v41, v109, v40
	v_fmamk_f32 v32, v69, 0xbc000000, v32
	v_fmamk_f32 v35, v69, 0xbc000000, v35
	v_fmac_f32_e32 v34, 0xbc000000, v69
	s_add_i32 s70, s70, s64
	s_waitcnt lgkmcnt(0)
	v_add_f32_e32 v40, v40, v41
	ds_bpermute_b32 v41, v154, v40
	s_waitcnt vmcnt(1)
	v_and_b32_e32 v45, 0xffff0000, v80
	v_lshlrev_b32_e32 v48, 16, v81
	v_and_b32_e32 v49, 0xffff0000, v81
	s_cmpk_gt_i32 s70, 0x41f
	s_waitcnt lgkmcnt(0)
	v_add_f32_e32 v40, v40, v41
	v_fmamk_f32 v40, v40, 0x3c000000, v163
	v_mul_f32_e32 v41, 0x4b800000, v40
	v_cmp_gt_f32_e32 vcc, s2, v40
	s_nop 1
	v_cndmask_b32_e32 v40, v40, v41, vcc
	v_rsq_f32_e32 v40, v40
	s_nop 0
	v_mul_f32_e32 v41, 0x45800000, v40
	v_cndmask_b32_e32 v40, v40, v41, vcc
	v_lshlrev_b32_e32 v41, 16, v80
	v_mul_f32_e32 v41, 0xbfb8aa3b, v41
	v_exp_f32_e32 v41, v41
	v_lshlrev_b64 v[80:81], 11, v[64:65]
	v_add_f32_e32 v41, 1.0, v41
	v_rcp_f32_e32 v44, v41
	v_mul_f32_e32 v41, 0xbfb8aa3b, v45
	v_mul_f32_e32 v45, 0xbfb8aa3b, v48
	v_exp_f32_e32 v45, v45
	v_mul_f32_e32 v48, 0xbfb8aa3b, v49
	v_exp_f32_e32 v41, v41
	v_exp_f32_e32 v48, v48
	v_add_f32_e32 v45, 1.0, v45
	v_rcp_f32_e32 v74, v45
	v_add_f32_e32 v41, 1.0, v41
	v_add_f32_e32 v45, 1.0, v48
	v_rcp_f32_e32 v75, v45
	v_rcp_f32_e32 v45, v41
	v_lshl_add_u64 v[48:49], v[78:79], 0, s[40:41]
	v_mov_b32_e32 v78, v6
	v_pk_mul_f32 v[62:63], v[62:63], v[74:75]
	v_pk_mul_f32 v[44:45], v[76:77], v[44:45]
	v_pk_mul_f32 v[62:63], v[62:63], v[40:41] op_sel_hi:[1,0]
	v_pk_mul_f32 v[44:45], v[44:45], v[40:41] op_sel_hi:[1,0]
	s_waitcnt vmcnt(0)
	v_pk_mul_f32 v[62:63], v[72:73], v[62:63]
	v_pk_mul_f32 v[44:45], v[70:71], v[44:45]
	v_cvt_pk_bf16_f32 v71, v62, v63
	v_cvt_pk_bf16_f32 v70, v44, v45
	v_lshl_add_u64 v[44:45], s[10:11], 0, v[80:81]
	v_lshl_add_u64 v[44:45], v[44:45], 0, s[96:97]
	v_lshl_add_u64 v[44:45], v[44:45], 0, v[128:129]
	global_store_dwordx2 v[44:45], v[70:71], off
	global_load_dwordx2 v[62:63], v[48:49], off offset:32
	s_nop 0
	global_load_dwordx4 v[70:73], v68, s[30:31] offset:64
	v_mov_b32_e32 v76, v5
	v_mov_b32_e32 v77, v1
	v_mov_b32_e32 v79, v2
	v_mov_b32_e32 v80, v7
	v_mov_b32_e32 v81, v3
	s_waitcnt vmcnt(1)
	v_lshlrev_b32_e32 v41, 16, v62
	v_mul_f32_e32 v41, 0xbfb8aa3b, v41
	v_exp_f32_e32 v41, v41
	v_and_b32_e32 v65, 0xffff0000, v62
	v_lshlrev_b32_e32 v74, 16, v63
	v_and_b32_e32 v63, 0xffff0000, v63
	v_add_f32_e32 v41, 1.0, v41
	v_rcp_f32_e32 v62, v41
	v_mul_f32_e32 v41, 0xbfb8aa3b, v65
	v_mul_f32_e32 v65, 0xbfb8aa3b, v74
	v_mul_f32_e32 v63, 0xbfb8aa3b, v63
	v_exp_f32_e32 v41, v41
	v_exp_f32_e32 v65, v65
	v_exp_f32_e32 v63, v63
	v_add_f32_e32 v41, 1.0, v41
	v_add_f32_e32 v65, 1.0, v65
	v_add_f32_e32 v63, 1.0, v63
	v_rcp_f32_e32 v74, v65
	v_rcp_f32_e32 v75, v63
	v_rcp_f32_e32 v63, v41
	v_pk_mul_f32 v[58:59], v[58:59], v[74:75]
	v_pk_mul_f32 v[60:61], v[60:61], v[62:63]
	v_pk_mul_f32 v[58:59], v[58:59], v[40:41] op_sel_hi:[1,0]
	v_pk_mul_f32 v[60:61], v[60:61], v[40:41] op_sel_hi:[1,0]
	s_waitcnt vmcnt(0)
	v_pk_mul_f32 v[58:59], v[72:73], v[58:59]
	v_pk_mul_f32 v[60:61], v[70:71], v[60:61]
	v_mov_b32_e32 v73, v11
	v_cvt_pk_bf16_f32 v60, v60, v61
	v_cvt_pk_bf16_f32 v61, v58, v59
	global_store_dwordx2 v[44:45], v[60:61], off offset:32
	global_load_dwordx2 v[62:63], v[48:49], off offset:64
	s_nop 0
	global_load_dwordx4 v[58:61], v68, s[30:31] offset:128
	v_mov_b32_e32 v74, v4
	v_mov_b32_e32 v75, v0
	s_waitcnt vmcnt(1)
	v_lshlrev_b32_e32 v41, 16, v62
	v_and_b32_e32 v62, 0xffff0000, v62
	v_lshlrev_b32_e32 v65, 16, v63
	v_and_b32_e32 v63, 0xffff0000, v63
	v_mul_f32_e32 v41, 0xbfb8aa3b, v41
	v_mul_f32_e32 v62, 0xbfb8aa3b, v62
	v_mul_f32_e32 v65, 0xbfb8aa3b, v65
	v_mul_f32_e32 v63, 0xbfb8aa3b, v63
	v_exp_f32_e32 v41, v41
	v_exp_f32_e32 v62, v62
	v_exp_f32_e32 v65, v65
	v_exp_f32_e32 v63, v63
	v_add_f32_e32 v41, 1.0, v41
	v_add_f32_e32 v72, 1.0, v62
	v_add_f32_e32 v65, 1.0, v65
	v_add_f32_e32 v63, 1.0, v63
	v_rcp_f32_e32 v62, v41
	v_rcp_f32_e32 v70, v65
	v_rcp_f32_e32 v71, v63
	v_rcp_f32_e32 v63, v72
	v_mov_b32_e32 v72, v15
	v_pk_mul_f32 v[54:55], v[54:55], v[70:71]
	v_pk_mul_f32 v[62:63], v[82:83], v[62:63]
	v_pk_mul_f32 v[54:55], v[54:55], v[40:41] op_sel_hi:[1,0]
	v_pk_mul_f32 v[62:63], v[62:63], v[40:41] op_sel_hi:[1,0]
	s_waitcnt vmcnt(0)
	v_pk_mul_f32 v[54:55], v[60:61], v[54:55]
	v_pk_mul_f32 v[58:59], v[58:59], v[62:63]
	v_mov_b32_e32 v70, v14
	v_cvt_pk_bf16_f32 v58, v58, v59
	v_cvt_pk_bf16_f32 v59, v54, v55
	global_store_dwordx2 v[44:45], v[58:59], off offset:64
	global_load_dwordx2 v[54:55], v[48:49], off offset:96
	s_nop 0
	global_load_dwordx4 v[58:61], v68, s[30:31] offset:192
	v_mov_b32_e32 v71, v10
	s_waitcnt vmcnt(1)
	v_lshlrev_b32_e32 v41, 16, v54
	v_and_b32_e32 v54, 0xffff0000, v54
	v_lshlrev_b32_e32 v62, 16, v55
	v_and_b32_e32 v55, 0xffff0000, v55
	v_mul_f32_e32 v41, 0xbfb8aa3b, v41
	v_mul_f32_e32 v54, 0xbfb8aa3b, v54
	v_mul_f32_e32 v62, 0xbfb8aa3b, v62
	v_mul_f32_e32 v55, 0xbfb8aa3b, v55
	v_exp_f32_e32 v41, v41
	v_exp_f32_e32 v54, v54
	v_exp_f32_e32 v62, v62
	v_exp_f32_e32 v55, v55
	v_add_f32_e32 v41, 1.0, v41
	v_add_f32_e32 v65, 1.0, v54
	v_add_f32_e32 v62, 1.0, v62
	v_add_f32_e32 v55, 1.0, v55
	v_rcp_f32_e32 v54, v41
	v_rcp_f32_e32 v62, v62
	v_rcp_f32_e32 v63, v55
	v_rcp_f32_e32 v55, v65
	v_pk_mul_f32 v[50:51], v[50:51], v[62:63]
	v_pk_mul_f32 v[54:55], v[66:67], v[54:55]
	v_pk_mul_f32 v[50:51], v[50:51], v[40:41] op_sel_hi:[1,0]
	v_pk_mul_f32 v[54:55], v[54:55], v[40:41] op_sel_hi:[1,0]
	s_waitcnt vmcnt(0)
	v_pk_mul_f32 v[50:51], v[60:61], v[50:51]
	v_pk_mul_f32 v[54:55], v[58:59], v[54:55]
	v_mov_b32_e32 v63, v8
	v_cvt_pk_bf16_f32 v54, v54, v55
	v_cvt_pk_bf16_f32 v55, v50, v51
	global_store_dwordx2 v[44:45], v[54:55], off offset:96
	global_load_dwordx2 v[50:51], v[48:49], off offset:128
	global_load_dwordx4 v[58:61], v68, s[30:31] offset:256
	v_mov_b32_e32 v66, v13
	v_mov_b32_e32 v67, v9
	s_waitcnt vmcnt(1)
	v_lshlrev_b32_e32 v41, 16, v50
	v_and_b32_e32 v50, 0xffff0000, v50
	v_lshlrev_b32_e32 v54, 16, v51
	v_and_b32_e32 v51, 0xffff0000, v51
	v_mul_f32_e32 v41, 0xbfb8aa3b, v41
	v_mul_f32_e32 v50, 0xbfb8aa3b, v50
	v_mul_f32_e32 v54, 0xbfb8aa3b, v54
	v_mul_f32_e32 v51, 0xbfb8aa3b, v51
	v_exp_f32_e32 v41, v41
	v_exp_f32_e32 v50, v50
	v_exp_f32_e32 v54, v54
	v_exp_f32_e32 v51, v51
	v_add_f32_e32 v41, 1.0, v41
	v_add_f32_e32 v62, 1.0, v50
	v_add_f32_e32 v54, 1.0, v54
	v_add_f32_e32 v51, 1.0, v51
	v_rcp_f32_e32 v50, v41
	v_rcp_f32_e32 v54, v54
	v_rcp_f32_e32 v55, v51
	v_rcp_f32_e32 v51, v62
	v_mov_b32_e32 v62, v12
	v_pk_mul_f32 v[46:47], v[46:47], v[54:55]
	v_pk_mul_f32 v[50:51], v[56:57], v[50:51]
	v_pk_mul_f32 v[46:47], v[46:47], v[40:41] op_sel_hi:[1,0]
	v_pk_mul_f32 v[50:51], v[50:51], v[40:41] op_sel_hi:[1,0]
	s_waitcnt vmcnt(0)
	v_pk_mul_f32 v[46:47], v[60:61], v[46:47]
	v_pk_mul_f32 v[50:51], v[58:59], v[50:51]
	v_mov_b32_e32 v59, v18
	v_cvt_pk_bf16_f32 v50, v50, v51
	v_cvt_pk_bf16_f32 v51, v46, v47
	global_store_dwordx2 v[44:45], v[50:51], off offset:128
	global_load_dwordx2 v[46:47], v[48:49], off offset:160
	global_load_dwordx4 v[54:57], v68, s[30:31] offset:320
	v_mov_b32_e32 v60, v23
	v_mov_b32_e32 v61, v19
	s_waitcnt vmcnt(1)
	v_lshlrev_b32_e32 v41, 16, v46
	v_and_b32_e32 v46, 0xffff0000, v46
	v_lshlrev_b32_e32 v50, 16, v47
	v_and_b32_e32 v47, 0xffff0000, v47
	v_mul_f32_e32 v41, 0xbfb8aa3b, v41
	v_mul_f32_e32 v46, 0xbfb8aa3b, v46
	v_mul_f32_e32 v50, 0xbfb8aa3b, v50
	v_mul_f32_e32 v47, 0xbfb8aa3b, v47
	v_exp_f32_e32 v41, v41
	v_exp_f32_e32 v46, v46
	v_exp_f32_e32 v50, v50
	v_exp_f32_e32 v47, v47
	v_add_f32_e32 v41, 1.0, v41
	v_add_f32_e32 v58, 1.0, v46
	v_add_f32_e32 v50, 1.0, v50
	v_add_f32_e32 v47, 1.0, v47
	v_rcp_f32_e32 v46, v41
	v_rcp_f32_e32 v50, v50
	v_rcp_f32_e32 v51, v47
	v_rcp_f32_e32 v47, v58
	v_mov_b32_e32 v58, v22
	v_pk_mul_f32 v[42:43], v[42:43], v[50:51]
	v_pk_mul_f32 v[46:47], v[52:53], v[46:47]
	v_pk_mul_f32 v[42:43], v[40:41], v[42:43] op_sel_hi:[0,1]
	v_pk_mul_f32 v[46:47], v[40:41], v[46:47] op_sel_hi:[0,1]
	s_waitcnt vmcnt(0)
	v_pk_mul_f32 v[42:43], v[56:57], v[42:43]
	v_pk_mul_f32 v[46:47], v[54:55], v[46:47]
	v_mov_b32_e32 v55, v16
	v_cvt_pk_bf16_f32 v46, v46, v47
	v_cvt_pk_bf16_f32 v47, v42, v43
	global_store_dwordx2 v[44:45], v[46:47], off offset:160
	global_load_dwordx2 v[42:43], v[48:49], off offset:192
	global_load_dwordx4 v[50:53], v68, s[30:31] offset:384
	v_mov_b32_e32 v56, v21
	v_mov_b32_e32 v57, v17
	s_waitcnt vmcnt(1)
	v_lshlrev_b32_e32 v41, 16, v42
	v_and_b32_e32 v42, 0xffff0000, v42
	v_lshlrev_b32_e32 v46, 16, v43
	v_and_b32_e32 v43, 0xffff0000, v43
	v_mul_f32_e32 v41, 0xbfb8aa3b, v41
	v_mul_f32_e32 v42, 0xbfb8aa3b, v42
	v_mul_f32_e32 v46, 0xbfb8aa3b, v46
	v_mul_f32_e32 v43, 0xbfb8aa3b, v43
	v_exp_f32_e32 v41, v41
	v_exp_f32_e32 v42, v42
	v_exp_f32_e32 v46, v46
	v_exp_f32_e32 v43, v43
	v_add_f32_e32 v41, 1.0, v41
	v_add_f32_e32 v54, 1.0, v42
	v_add_f32_e32 v46, 1.0, v46
	v_add_f32_e32 v43, 1.0, v43
	v_rcp_f32_e32 v42, v41
	v_rcp_f32_e32 v46, v46
	v_rcp_f32_e32 v47, v43
	v_rcp_f32_e32 v43, v54
	v_mov_b32_e32 v54, v20
	v_pk_mul_f32 v[38:39], v[38:39], v[46:47]
	v_pk_mul_f32 v[36:37], v[36:37], v[42:43]
	v_pk_mul_f32 v[38:39], v[40:41], v[38:39] op_sel_hi:[0,1]
	v_pk_mul_f32 v[36:37], v[40:41], v[36:37] op_sel_hi:[0,1]
	s_waitcnt vmcnt(0)
	v_pk_mul_f32 v[38:39], v[52:53], v[38:39]
	v_pk_mul_f32 v[36:37], v[50:51], v[36:37]
	v_mov_b32_e32 v42, v29
	v_cvt_pk_bf16_f32 v36, v36, v37
	v_cvt_pk_bf16_f32 v37, v38, v39
	global_store_dwordx2 v[44:45], v[36:37], off offset:192
	global_load_dwordx2 v[36:37], v[48:49], off offset:224
	v_mov_b32_e32 v38, v28
	global_load_dwordx4 v[46:49], v68, s[30:31] offset:448
	v_mov_b32_e32 v39, v24
	v_mov_b32_e32 v43, v25
	v_mov_b32_e32 v50, v30
	v_mov_b32_e32 v51, v26
	v_pk_add_f32 v[38:39], v[38:39], v[42:43]
	v_mov_b32_e32 v52, v31
	v_mov_b32_e32 v53, v27
	v_pk_add_f32 v[38:39], v[50:51], v[38:39]
	v_pk_add_f32 v[42:43], v[54:55], v[56:57]
	v_pk_add_f32 v[38:39], v[52:53], v[38:39]
	v_pk_add_f32 v[42:43], v[58:59], v[42:43]
	v_add_f32_e32 v38, 0, v38
	v_pk_add_f32 v[54:55], v[62:63], v[66:67]
	v_pk_add_f32 v[42:43], v[60:61], v[42:43]
	v_add_f32_e32 v38, v38, v39
	v_pk_add_f32 v[50:51], v[70:71], v[54:55]
	v_add_f32_e32 v38, v38, v42
	v_pk_add_f32 v[56:57], v[74:75], v[76:77]
	v_pk_add_f32 v[50:51], v[72:73], v[50:51]
	v_add_f32_e32 v38, v38, v43
	v_pk_add_f32 v[54:55], v[78:79], v[56:57]
	v_add_f32_e32 v38, v38, v50
	v_pk_add_f32 v[52:53], v[80:81], v[54:55]
	v_add_f32_e32 v38, v38, v51
	v_add_f32_e32 v38, v38, v52
	v_add_f32_e32 v41, v38, v53
	v_add_u32_e32 v62, 16, v64
	ds_bpermute_b32 v50, v109, v41
	v_ashrrev_i32_e32 v63, 31, v62
	v_lshlrev_b64 v[38:39], 14, v[62:63]
	v_lshl_add_u64 v[38:39], s[52:53], 0, v[38:39]
	v_lshl_add_u64 v[38:39], v[38:39], 0, s[96:97]
	v_lshl_add_u64 v[42:43], v[38:39], 0, v[128:129]
	s_waitcnt lgkmcnt(0)
	v_add_f32_e32 v38, v41, v50
	ds_bpermute_b32 v39, v154, v38
	v_add_co_u32_e32 v50, vcc, s38, v42
	s_waitcnt lgkmcnt(0)
	v_add_f32_e32 v38, v38, v39
	v_fmamk_f32 v54, v38, 0xbc000000, v28
	v_fmamk_f32 v55, v38, 0xbc000000, v29
	v_addc_co_u32_e32 v51, vcc, 0, v43, vcc
	v_mul_f32_e32 v39, v55, v55
	v_fmamk_f32 v30, v38, 0xbc000000, v30
	v_fmac_f32_e32 v39, v54, v54
	v_fmac_f32_e32 v31, 0xbc000000, v38
	v_fmac_f32_e32 v39, v30, v30
	v_fmac_f32_e32 v39, v31, v31
	v_fmamk_f32 v26, v38, 0xbc000000, v26
	v_fmac_f32_e32 v27, 0xbc000000, v38
	v_fmamk_f32 v22, v38, 0xbc000000, v22
	v_fmac_f32_e32 v23, 0xbc000000, v38
	v_fmamk_f32 v18, v38, 0xbc000000, v18
	v_fmac_f32_e32 v19, 0xbc000000, v38
	v_fmamk_f32 v14, v38, 0xbc000000, v14
	v_fmac_f32_e32 v15, 0xbc000000, v38
	v_mul_f32_e32 v52, 0x3c000000, v38
	v_fmamk_f32 v10, v38, 0xbc000000, v10
	v_fmac_f32_e32 v11, 0xbc000000, v38
	s_waitcnt vmcnt(1)
	v_lshlrev_b32_e32 v28, 16, v36
	v_and_b32_e32 v29, 0xffff0000, v36
	v_lshlrev_b32_e32 v36, 16, v37
	v_and_b32_e32 v37, 0xffff0000, v37
	v_mul_f32_e32 v28, 0xbfb8aa3b, v28
	v_mul_f32_e32 v29, 0xbfb8aa3b, v29
	v_mul_f32_e32 v36, 0xbfb8aa3b, v36
	v_mul_f32_e32 v37, 0xbfb8aa3b, v37
	v_exp_f32_e32 v28, v28
	v_exp_f32_e32 v29, v29
	v_exp_f32_e32 v36, v36
	v_exp_f32_e32 v37, v37
	v_add_f32_e32 v28, 1.0, v28
	v_add_f32_e32 v29, 1.0, v29
	v_add_f32_e32 v36, 1.0, v36
	v_add_f32_e32 v37, 1.0, v37
	v_rcp_f32_e32 v28, v28
	v_rcp_f32_e32 v36, v36
	v_rcp_f32_e32 v37, v37
	v_rcp_f32_e32 v29, v29
	v_pk_mul_f32 v[34:35], v[34:35], v[36:37]
	v_pk_mul_f32 v[28:29], v[32:33], v[28:29]
	v_pk_mul_f32 v[32:33], v[40:41], v[34:35] op_sel_hi:[0,1]
	v_pk_mul_f32 v[28:29], v[40:41], v[28:29] op_sel_hi:[0,1]
	s_waitcnt vmcnt(0)
	v_pk_mul_f32 v[32:33], v[48:49], v[32:33]
	v_pk_mul_f32 v[28:29], v[46:47], v[28:29]
	v_pk_add_f32 v[46:47], v[2:3], v[52:53] op_sel_hi:[1,0] neg_lo:[0,1] neg_hi:[0,1]
	v_cvt_pk_bf16_f32 v28, v28, v29
	v_cvt_pk_bf16_f32 v29, v32, v33
	global_store_dwordx2 v[44:45], v[28:29], off offset:224
	global_load_dwordx2 v[40:41], v[50:51], off offset:2048
	global_load_dwordx4 v[34:37], v68, s[30:31]
	v_fmamk_f32 v44, v38, 0xbc000000, v24
	v_fmamk_f32 v45, v38, 0xbc000000, v25
	v_fmac_f32_e32 v39, v44, v44
	v_fmac_f32_e32 v39, v45, v45
	v_fmac_f32_e32 v39, v26, v26
	v_fmamk_f32 v32, v38, 0xbc000000, v20
	v_fmac_f32_e32 v39, v27, v27
	v_fmamk_f32 v33, v38, 0xbc000000, v21
	v_fmac_f32_e32 v39, v32, v32
	v_fmac_f32_e32 v39, v33, v33
	v_fmac_f32_e32 v39, v22, v22
	v_fmamk_f32 v28, v38, 0xbc000000, v16
	v_fmac_f32_e32 v39, v23, v23
	v_fmamk_f32 v29, v38, 0xbc000000, v17
	v_fmac_f32_e32 v39, v28, v28
	v_fmac_f32_e32 v39, v29, v29
	v_fmac_f32_e32 v39, v18, v18
	v_fmamk_f32 v24, v38, 0xbc000000, v12
	v_fmac_f32_e32 v39, v19, v19
	v_fmamk_f32 v25, v38, 0xbc000000, v13
	v_fmac_f32_e32 v39, v24, v24
	v_fmac_f32_e32 v39, v25, v25
	v_fmac_f32_e32 v39, v14, v14
	v_fmamk_f32 v16, v38, 0xbc000000, v8
	v_fmac_f32_e32 v39, v15, v15
	v_fmamk_f32 v17, v38, 0xbc000000, v9
	v_fmac_f32_e32 v39, v16, v16
	v_fmac_f32_e32 v39, v17, v17
	v_pk_add_f32 v[8:9], v[4:5], v[52:53] op_sel_hi:[1,0] neg_lo:[0,1] neg_hi:[0,1]
	v_fmac_f32_e32 v39, v10, v10
	v_pk_mul_f32 v[8:9], v[8:9], v[8:9]
	v_fmac_f32_e32 v39, v11, v11
	v_pk_add_f32 v[12:13], v[6:7], v[52:53] op_sel_hi:[1,0] neg_lo:[0,1] neg_hi:[0,1]
	v_add_f32_e32 v8, v8, v39
	v_pk_mul_f32 v[12:13], v[12:13], v[12:13]
	v_add_f32_e32 v8, v9, v8
	v_pk_add_f32 v[20:21], v[0:1], v[52:53] op_sel_hi:[1,0] neg_lo:[0,1] neg_hi:[0,1]
	v_add_f32_e32 v8, v12, v8
	v_pk_mul_f32 v[20:21], v[20:21], v[20:21]
	v_add_f32_e32 v8, v13, v8
	v_add_f32_e32 v8, v20, v8
	v_pk_mul_f32 v[46:47], v[46:47], v[46:47]
	v_add_f32_e32 v8, v21, v8
	v_add_f32_e32 v8, v46, v8
	v_add_f32_e32 v12, v47, v8
	ds_bpermute_b32 v13, v109, v12
	v_lshl_add_u64 v[20:21], v[42:43], 0, s[40:41]
	v_lshlrev_b64 v[8:9], 11, v[62:63]
	v_lshl_add_u64 v[8:9], s[10:11], 0, v[8:9]
	v_lshl_add_u64 v[8:9], v[8:9], 0, s[96:97]
	s_waitcnt lgkmcnt(0)
	v_add_f32_e32 v12, v12, v13
	ds_bpermute_b32 v13, v154, v12
	v_lshl_add_u64 v[8:9], v[8:9], 0, v[128:129]
	v_fmamk_f32 v5, v38, 0xbc000000, v5
	v_fmamk_f32 v4, v38, 0xbc000000, v4
	v_fmamk_f32 v7, v38, 0xbc000000, v7
	s_waitcnt lgkmcnt(0)
	v_add_f32_e32 v12, v12, v13
	v_fmamk_f32 v12, v12, 0x3c000000, v163
	v_mul_f32_e32 v13, 0x4b800000, v12
	v_cmp_gt_f32_e32 vcc, s2, v12
	v_fmac_f32_e32 v6, 0xbc000000, v38
	v_fmamk_f32 v1, v38, 0xbc000000, v1
	v_cndmask_b32_e32 v12, v12, v13, vcc
	v_rsq_f32_e32 v12, v12
	v_fmamk_f32 v0, v38, 0xbc000000, v0
	v_fmamk_f32 v3, v38, 0xbc000000, v3
	v_fmac_f32_e32 v2, 0xbc000000, v38
	s_waitcnt vmcnt(1)
	v_lshlrev_b32_e32 v13, 16, v40
	v_and_b32_e32 v39, 0xffff0000, v40
	v_lshlrev_b32_e32 v40, 16, v41
	v_and_b32_e32 v41, 0xffff0000, v41
	v_mul_f32_e32 v13, 0xbfb8aa3b, v13
	v_mul_f32_e32 v39, 0xbfb8aa3b, v39
	v_mul_f32_e32 v40, 0xbfb8aa3b, v40
	v_mul_f32_e32 v41, 0xbfb8aa3b, v41
	v_exp_f32_e32 v13, v13
	v_exp_f32_e32 v39, v39
	v_exp_f32_e32 v40, v40
	v_exp_f32_e32 v41, v41
	v_add_f32_e32 v13, 1.0, v13
	v_add_f32_e32 v39, 1.0, v39
	v_add_f32_e32 v42, 1.0, v40
	v_add_f32_e32 v41, 1.0, v41
	v_rcp_f32_e32 v40, v13
	v_rcp_f32_e32 v42, v42
	v_rcp_f32_e32 v43, v41
	v_rcp_f32_e32 v41, v39
	v_mul_f32_e32 v13, 0x45800000, v12
	v_cndmask_b32_e32 v12, v12, v13, vcc
	v_pk_mul_f32 v[30:31], v[30:31], v[42:43]
	v_pk_mul_f32 v[40:41], v[54:55], v[40:41]
	v_pk_mul_f32 v[30:31], v[30:31], v[12:13] op_sel_hi:[1,0]
	v_pk_mul_f32 v[40:41], v[40:41], v[12:13] op_sel_hi:[1,0]
	s_waitcnt vmcnt(0)
	v_pk_mul_f32 v[30:31], v[36:37], v[30:31]
	v_pk_mul_f32 v[34:35], v[34:35], v[40:41]
	s_nop 0
	v_cvt_pk_bf16_f32 v34, v34, v35
	v_cvt_pk_bf16_f32 v35, v30, v31
	global_store_dwordx2 v[8:9], v[34:35], off
	global_load_dwordx2 v[30:31], v[20:21], off offset:32
	s_nop 0
	global_load_dwordx4 v[34:37], v68, s[30:31] offset:64
	s_waitcnt vmcnt(1)
	v_lshlrev_b32_e32 v13, 16, v30
	v_and_b32_e32 v30, 0xffff0000, v30
	v_lshlrev_b32_e32 v39, 16, v31
	v_and_b32_e32 v31, 0xffff0000, v31
	v_mul_f32_e32 v13, 0xbfb8aa3b, v13
	v_mul_f32_e32 v30, 0xbfb8aa3b, v30
	v_mul_f32_e32 v39, 0xbfb8aa3b, v39
	v_mul_f32_e32 v31, 0xbfb8aa3b, v31
	v_exp_f32_e32 v13, v13
	v_exp_f32_e32 v30, v30
	v_exp_f32_e32 v39, v39
	v_exp_f32_e32 v31, v31
	v_add_f32_e32 v13, 1.0, v13
	v_add_f32_e32 v42, 1.0, v30
	v_add_f32_e32 v39, 1.0, v39
	v_add_f32_e32 v31, 1.0, v31
	v_rcp_f32_e32 v30, v13
	v_rcp_f32_e32 v40, v39
	v_rcp_f32_e32 v41, v31
	v_rcp_f32_e32 v31, v42
	v_pk_mul_f32 v[26:27], v[26:27], v[40:41]
	v_pk_mul_f32 v[30:31], v[44:45], v[30:31]
	v_pk_mul_f32 v[26:27], v[26:27], v[12:13] op_sel_hi:[1,0]
	v_pk_mul_f32 v[30:31], v[30:31], v[12:13] op_sel_hi:[1,0]
	s_waitcnt vmcnt(0)
	v_pk_mul_f32 v[26:27], v[36:37], v[26:27]
	v_pk_mul_f32 v[30:31], v[34:35], v[30:31]
	s_nop 0
	v_cvt_pk_bf16_f32 v30, v30, v31
	v_cvt_pk_bf16_f32 v31, v26, v27
	global_store_dwordx2 v[8:9], v[30:31], off offset:32
	global_load_dwordx2 v[26:27], v[20:21], off offset:64
	global_load_dwordx4 v[34:37], v68, s[30:31] offset:128
	s_waitcnt vmcnt(1)
	v_lshlrev_b32_e32 v13, 16, v26
	v_and_b32_e32 v26, 0xffff0000, v26
	v_lshlrev_b32_e32 v30, 16, v27
	v_and_b32_e32 v27, 0xffff0000, v27
	v_mul_f32_e32 v13, 0xbfb8aa3b, v13
	v_mul_f32_e32 v26, 0xbfb8aa3b, v26
	v_mul_f32_e32 v30, 0xbfb8aa3b, v30
	v_mul_f32_e32 v27, 0xbfb8aa3b, v27
	v_exp_f32_e32 v13, v13
	v_exp_f32_e32 v26, v26
	v_exp_f32_e32 v30, v30
	v_exp_f32_e32 v27, v27
	v_add_f32_e32 v13, 1.0, v13
	v_add_f32_e32 v39, 1.0, v26
	v_add_f32_e32 v30, 1.0, v30
	v_add_f32_e32 v27, 1.0, v27
	v_rcp_f32_e32 v26, v13
	v_rcp_f32_e32 v30, v30
	v_rcp_f32_e32 v31, v27
	v_rcp_f32_e32 v27, v39
	v_pk_mul_f32 v[22:23], v[22:23], v[30:31]
	v_pk_mul_f32 v[26:27], v[32:33], v[26:27]
	v_pk_mul_f32 v[22:23], v[22:23], v[12:13] op_sel_hi:[1,0]
	v_pk_mul_f32 v[26:27], v[26:27], v[12:13] op_sel_hi:[1,0]
	s_waitcnt vmcnt(0)
	v_pk_mul_f32 v[22:23], v[36:37], v[22:23]
	v_pk_mul_f32 v[26:27], v[34:35], v[26:27]
	s_nop 0
	v_cvt_pk_bf16_f32 v26, v26, v27
	v_cvt_pk_bf16_f32 v27, v22, v23
	global_store_dwordx2 v[8:9], v[26:27], off offset:64
	global_load_dwordx2 v[22:23], v[20:21], off offset:96
	global_load_dwordx4 v[30:33], v68, s[30:31] offset:192
	s_waitcnt vmcnt(1)
	v_lshlrev_b32_e32 v13, 16, v22
	v_and_b32_e32 v22, 0xffff0000, v22
	v_lshlrev_b32_e32 v26, 16, v23
	v_and_b32_e32 v23, 0xffff0000, v23
	v_mul_f32_e32 v13, 0xbfb8aa3b, v13
	v_mul_f32_e32 v22, 0xbfb8aa3b, v22
	v_mul_f32_e32 v26, 0xbfb8aa3b, v26
	v_mul_f32_e32 v23, 0xbfb8aa3b, v23
	v_exp_f32_e32 v13, v13
	v_exp_f32_e32 v22, v22
	v_exp_f32_e32 v26, v26
	v_exp_f32_e32 v23, v23
	v_add_f32_e32 v13, 1.0, v13
	v_add_f32_e32 v34, 1.0, v22
	v_add_f32_e32 v26, 1.0, v26
	v_add_f32_e32 v23, 1.0, v23
	v_rcp_f32_e32 v22, v13
	v_rcp_f32_e32 v26, v26
	v_rcp_f32_e32 v27, v23
	v_rcp_f32_e32 v23, v34
	v_pk_mul_f32 v[18:19], v[18:19], v[26:27]
	v_pk_mul_f32 v[22:23], v[28:29], v[22:23]
	v_pk_mul_f32 v[18:19], v[18:19], v[12:13] op_sel_hi:[1,0]
	v_pk_mul_f32 v[22:23], v[22:23], v[12:13] op_sel_hi:[1,0]
	s_waitcnt vmcnt(0)
	v_pk_mul_f32 v[18:19], v[32:33], v[18:19]
	v_pk_mul_f32 v[22:23], v[30:31], v[22:23]
	s_nop 0
	v_cvt_pk_bf16_f32 v22, v22, v23
	v_cvt_pk_bf16_f32 v23, v18, v19
	global_store_dwordx2 v[8:9], v[22:23], off offset:96
	global_load_dwordx2 v[18:19], v[20:21], off offset:128
	global_load_dwordx4 v[26:29], v68, s[30:31] offset:256
	s_waitcnt vmcnt(1)
	v_lshlrev_b32_e32 v13, 16, v18
	v_and_b32_e32 v18, 0xffff0000, v18
	v_lshlrev_b32_e32 v22, 16, v19
	v_and_b32_e32 v19, 0xffff0000, v19
	v_mul_f32_e32 v13, 0xbfb8aa3b, v13
	v_mul_f32_e32 v18, 0xbfb8aa3b, v18
	v_mul_f32_e32 v22, 0xbfb8aa3b, v22
	v_mul_f32_e32 v19, 0xbfb8aa3b, v19
	v_exp_f32_e32 v13, v13
	v_exp_f32_e32 v18, v18
	v_exp_f32_e32 v22, v22
	v_exp_f32_e32 v19, v19
	v_add_f32_e32 v13, 1.0, v13
	v_add_f32_e32 v30, 1.0, v18
	v_add_f32_e32 v22, 1.0, v22
	v_add_f32_e32 v19, 1.0, v19
	v_rcp_f32_e32 v18, v13
	v_rcp_f32_e32 v22, v22
	v_rcp_f32_e32 v23, v19
	v_rcp_f32_e32 v19, v30
	v_pk_mul_f32 v[14:15], v[14:15], v[22:23]
	v_pk_mul_f32 v[18:19], v[24:25], v[18:19]
	v_pk_mul_f32 v[14:15], v[14:15], v[12:13] op_sel_hi:[1,0]
	v_pk_mul_f32 v[18:19], v[18:19], v[12:13] op_sel_hi:[1,0]
	s_waitcnt vmcnt(0)
	v_pk_mul_f32 v[14:15], v[28:29], v[14:15]
	v_pk_mul_f32 v[18:19], v[26:27], v[18:19]
	s_nop 0
	v_cvt_pk_bf16_f32 v18, v18, v19
	v_cvt_pk_bf16_f32 v19, v14, v15
	global_store_dwordx2 v[8:9], v[18:19], off offset:128
	global_load_dwordx2 v[14:15], v[20:21], off offset:160
	global_load_dwordx4 v[22:25], v68, s[30:31] offset:320
	s_waitcnt vmcnt(1)
	v_lshlrev_b32_e32 v13, 16, v14
	v_and_b32_e32 v14, 0xffff0000, v14
	v_lshlrev_b32_e32 v18, 16, v15
	v_and_b32_e32 v15, 0xffff0000, v15
	v_mul_f32_e32 v13, 0xbfb8aa3b, v13
	v_mul_f32_e32 v14, 0xbfb8aa3b, v14
	v_mul_f32_e32 v18, 0xbfb8aa3b, v18
	v_mul_f32_e32 v15, 0xbfb8aa3b, v15
	v_exp_f32_e32 v13, v13
	v_exp_f32_e32 v14, v14
	v_exp_f32_e32 v18, v18
	v_exp_f32_e32 v15, v15
	v_add_f32_e32 v13, 1.0, v13
	v_add_f32_e32 v26, 1.0, v14
	v_add_f32_e32 v18, 1.0, v18
	v_add_f32_e32 v15, 1.0, v15
	v_rcp_f32_e32 v14, v13
	v_rcp_f32_e32 v18, v18
	v_rcp_f32_e32 v19, v15
	v_rcp_f32_e32 v15, v26
	v_pk_mul_f32 v[10:11], v[10:11], v[18:19]
	v_pk_mul_f32 v[14:15], v[16:17], v[14:15]
	v_pk_mul_f32 v[10:11], v[12:13], v[10:11] op_sel_hi:[0,1]
	v_pk_mul_f32 v[14:15], v[12:13], v[14:15] op_sel_hi:[0,1]
	s_waitcnt vmcnt(0)
	v_pk_mul_f32 v[10:11], v[24:25], v[10:11]
	v_pk_mul_f32 v[14:15], v[22:23], v[14:15]
	s_nop 0
	v_cvt_pk_bf16_f32 v14, v14, v15
	v_cvt_pk_bf16_f32 v15, v10, v11
	global_store_dwordx2 v[8:9], v[14:15], off offset:160
	global_load_dwordx2 v[10:11], v[20:21], off offset:192
	s_nop 0
	global_load_dwordx4 v[14:17], v68, s[30:31] offset:384
	s_waitcnt vmcnt(1)
	v_lshlrev_b32_e32 v13, 16, v10
	v_and_b32_e32 v10, 0xffff0000, v10
	v_lshlrev_b32_e32 v18, 16, v11
	v_and_b32_e32 v11, 0xffff0000, v11
	v_mul_f32_e32 v13, 0xbfb8aa3b, v13
	v_mul_f32_e32 v10, 0xbfb8aa3b, v10
	v_mul_f32_e32 v18, 0xbfb8aa3b, v18
	v_mul_f32_e32 v11, 0xbfb8aa3b, v11
	v_exp_f32_e32 v13, v13
	v_exp_f32_e32 v10, v10
	v_exp_f32_e32 v18, v18
	v_exp_f32_e32 v11, v11
	v_add_f32_e32 v13, 1.0, v13
	v_add_f32_e32 v22, 1.0, v10
	v_add_f32_e32 v18, 1.0, v18
	v_add_f32_e32 v11, 1.0, v11
	v_rcp_f32_e32 v10, v13
	v_rcp_f32_e32 v18, v18
	v_rcp_f32_e32 v19, v11
	v_rcp_f32_e32 v11, v22
	v_pk_mul_f32 v[6:7], v[6:7], v[18:19]
	v_pk_mul_f32 v[4:5], v[4:5], v[10:11]
	v_pk_mul_f32 v[6:7], v[12:13], v[6:7] op_sel_hi:[0,1]
	v_pk_mul_f32 v[4:5], v[12:13], v[4:5] op_sel_hi:[0,1]
	s_waitcnt vmcnt(0)
	v_pk_mul_f32 v[6:7], v[16:17], v[6:7]
	v_pk_mul_f32 v[4:5], v[14:15], v[4:5]
	s_nop 0
	v_cvt_pk_bf16_f32 v4, v4, v5
	v_cvt_pk_bf16_f32 v5, v6, v7
	global_store_dwordx2 v[8:9], v[4:5], off offset:192
	global_load_dwordx2 v[10:11], v[20:21], off offset:224
	s_nop 0
	global_load_dwordx4 v[4:7], v68, s[30:31] offset:448
	s_waitcnt vmcnt(1)
	v_lshlrev_b32_e32 v13, 16, v10
	v_and_b32_e32 v10, 0xffff0000, v10
	v_lshlrev_b32_e32 v14, 16, v11
	v_and_b32_e32 v11, 0xffff0000, v11
	v_mul_f32_e32 v13, 0xbfb8aa3b, v13
	v_mul_f32_e32 v10, 0xbfb8aa3b, v10
	v_mul_f32_e32 v14, 0xbfb8aa3b, v14
	v_mul_f32_e32 v11, 0xbfb8aa3b, v11
	v_exp_f32_e32 v13, v13
	v_exp_f32_e32 v10, v10
	v_exp_f32_e32 v14, v14
	v_exp_f32_e32 v11, v11
	v_add_f32_e32 v13, 1.0, v13
	v_add_f32_e32 v16, 1.0, v10
	v_add_f32_e32 v14, 1.0, v14
	v_add_f32_e32 v11, 1.0, v11
	v_rcp_f32_e32 v10, v13
	v_rcp_f32_e32 v14, v14
	v_rcp_f32_e32 v15, v11
	v_rcp_f32_e32 v11, v16
	v_pk_mul_f32 v[2:3], v[2:3], v[14:15]
	v_pk_mul_f32 v[0:1], v[0:1], v[10:11]
	v_pk_mul_f32 v[2:3], v[12:13], v[2:3] op_sel_hi:[0,1]
	v_pk_mul_f32 v[0:1], v[12:13], v[0:1] op_sel_hi:[0,1]
	s_waitcnt vmcnt(0)
	v_pk_mul_f32 v[2:3], v[6:7], v[2:3]
	v_pk_mul_f32 v[0:1], v[4:5], v[0:1]
	s_nop 0
	v_cvt_pk_bf16_f32 v0, v0, v1
	v_cvt_pk_bf16_f32 v1, v2, v3
	global_store_dwordx2 v[8:9], v[0:1], off offset:224
	s_cbranch_scc1 .LBB1_806

.LBB1_106:
	s_or_b64 exec, exec, s[30:31]
	s_load_dwordx16 s[40:55], s[0:1], 0x140
	s_ashr_i32 s67, s66, 31
	s_lshl_b64 s[4:5], s[66:67], 11
	v_ashrrev_i32_e32 v93, 6, v64
	v_and_b32_e32 v155, 15, v64
	s_waitcnt lgkmcnt(0)
	s_add_u32 s6, s40, s4
	s_addc_u32 s7, s41, s5
	s_lshl_b32 s8, s2, 8
	v_bfe_u32 v92, v64, 4, 2
	s_add_u32 s6, s6, s8
	v_lshl_or_b32 v108, v93, 5, v155
	s_addc_u32 s7, s7, 0
	v_lshlrev_b32_e32 v128, 4, v92
	v_ashrrev_i32_e32 v109, 31, v108
	v_lshl_add_u64 v[0:1], s[6:7], 0, v[128:129]
	v_lshlrev_b64 v[2:3], 11, v[108:109]
	v_or_b32_e32 v106, 16, v108
	v_lshl_add_u64 v[2:3], v[0:1], 0, v[2:3]
	v_ashrrev_i32_e32 v107, 31, v106
	global_load_dwordx4 v[28:31], v[2:3], off
	global_load_dwordx4 v[20:23], v[2:3], off offset:64
	global_load_dwordx4 v[12:15], v[2:3], off offset:128
	global_load_dwordx4 v[4:7], v[2:3], off offset:192
	v_lshlrev_b64 v[2:3], 11, v[106:107]
	v_lshl_add_u64 v[0:1], v[0:1], 0, v[2:3]
	s_add_u32 s4, s42, s4
	global_load_dwordx4 v[24:27], v[0:1], off
	global_load_dwordx4 v[16:19], v[0:1], off offset:64
	global_load_dwordx4 v[8:11], v[0:1], off offset:128
	s_nop 0
	global_load_dwordx4 v[0:3], v[0:1], off offset:192
	s_addc_u32 s5, s43, s5
	s_load_dwordx16 s[40:55], s[0:1], 0x100
	v_ashrrev_i32_e32 v104, 4, v64
	s_add_u32 s4, s4, s8
	v_ashrrev_i32_e32 v105, 31, v104
	s_addc_u32 s5, s5, 0
	v_lshlrev_b64 v[32:33], 11, v[104:105]
	v_lshl_add_u64 v[32:33], s[4:5], 0, v[32:33]
	v_lshlrev_b32_e32 v34, 3, v64
	s_lshl_b64 s[4:5], s[66:67], 14
	v_and_b32_e32 v34, 0x78, v34
	s_waitcnt lgkmcnt(0)
	s_add_u32 s4, s52, s4
	v_lshlrev_b32_e32 v128, 1, v34
	s_addc_u32 s5, s53, s5
	v_lshl_add_u64 v[74:75], v[32:33], 0, v[128:129]
	s_add_u32 s4, s4, s8
	v_lshlrev_b32_e32 v32, 15, v64
	v_ashrrev_i32_e32 v34, 1, v64
	s_addc_u32 s5, s5, 0
	v_and_b32_e32 v32, 0x1f8000, v32
	v_mov_b32_e32 v33, v129
	v_and_b32_e32 v66, 0xffffffe0, v34
	v_lshl_add_u64 v[32:33], s[4:5], 0, v[32:33]
	v_ashrrev_i32_e32 v67, 31, v66
	v_lshl_add_u64 v[36:37], v[66:67], 1, v[32:33]
	s_mov_b64 s[4:5], 0x1000
	v_lshl_add_u64 v[38:39], v[36:37], 0, s[4:5]
	s_mov_b64 s[4:5], 0x5000
	v_lshl_add_u64 v[52:53], v[36:37], 0, s[4:5]
	s_movk_i32 s4, 0x1000
	v_add_co_u32_e64 v32, s[38:39], s4, v36
	s_movk_i32 s4, 0x5000
	s_nop 0
	v_addc_co_u32_e64 v33, s[38:39], 0, v37, s[38:39]
	v_add_co_u32_e64 v36, s[38:39], s4, v36
	global_load_dwordx4 v[56:59], v[32:33], off
	s_nop 0
	global_load_dwordx4 v[32:35], v[38:39], off offset:48
	global_load_dwordx4 v[40:43], v[38:39], off offset:32
	global_load_dwordx4 v[48:51], v[38:39], off offset:16
	v_addc_co_u32_e64 v37, s[38:39], 0, v37, s[38:39]
	global_load_dwordx4 v[60:63], v[36:37], off
	s_nop 0
	global_load_dwordx4 v[36:39], v[52:53], off offset:48
	global_load_dwordx4 v[44:47], v[52:53], off offset:32
	s_nop 0
	global_load_dwordx4 v[52:55], v[52:53], off offset:16
	v_mul_lo_u32 v65, v104, s3
	global_load_dwordx4 v[70:73], v[74:75], off
	v_lshlrev_b32_e32 v67, 4, v64
	v_add_u32_e32 v65, 16, v65
	v_and_b32_e32 v67, 0xf0, v67
	v_add_u32_e32 v107, v65, v67
	s_mov_b32 s4, 0x8000
	v_and_b32_e32 v65, 63, v64
	v_lshlrev_b32_e32 v65, 2, v65
	s_load_dwordx4 s[8:11], s[0:1], 0x1a0
	s_waitcnt vmcnt(8)
	v_and_b32_e32 v67, 0xffff, v56
	v_lshrrev_b32_e32 v56, 16, v56
	s_waitcnt vmcnt(4)
	v_lshl_or_b32 v67, v60, 16, v67
	s_waitcnt vmcnt(0)
	ds_write_b128 v107, v[70:73]
	v_add_co_u32_e64 v70, s[38:39], s4, v74
	s_mov_b32 s4, 0x10000
	s_nop 0
	v_addc_co_u32_e64 v71, s[38:39], 0, v75, s[38:39]
	global_load_dwordx4 v[204:207], v[70:71], off
	v_add_co_u32_e64 v70, s[38:39], s4, v74
	s_mov_b32 s4, 0x18000
	s_nop 0
	v_addc_co_u32_e64 v71, s[38:39], 0, v75, s[38:39]
	global_load_dwordx4 v[208:211], v[70:71], off
	v_add_co_u32_e64 v70, s[38:39], s4, v74
	s_mov_b32 s4, 0x20000
	s_nop 0
	v_addc_co_u32_e64 v71, s[38:39], 0, v75, s[38:39]
	global_load_dwordx4 v[216:219], v[70:71], off
	v_add_co_u32_e64 v70, s[38:39], s4, v74
	s_mov_b32 s4, 0x28000
	s_nop 0
	v_addc_co_u32_e64 v71, s[38:39], 0, v75, s[38:39]
	global_load_dwordx4 v[220:223], v[70:71], off
	v_add_co_u32_e64 v70, s[38:39], s4, v74
	s_mov_b32 s4, 0x30000
	s_nop 0
	v_addc_co_u32_e64 v71, s[38:39], 0, v75, s[38:39]
	global_load_dwordx4 v[224:227], v[70:71], off
	v_add_co_u32_e64 v70, s[38:39], s4, v74
	s_mov_b32 s4, 0x38000
	s_nop 0
	v_addc_co_u32_e64 v71, s[38:39], 0, v75, s[38:39]
	global_load_dwordx4 v[228:231], v[70:71], off
	v_add_co_u32_e64 v70, s[38:39], s4, v74
	s_mov_b32 s4, 0xffff0000
	s_nop 0
	v_addc_co_u32_e64 v71, s[38:39], 0, v75, s[38:39]
	global_load_dwordx4 v[232:235], v[70:71], off
	v_and_or_b32 v56, v60, s4, v56
	v_mul_lo_u32 v60, v66, s3
	v_add3_u32 v60, 16, v60, v65
	v_add_u32_e32 v65, 0x8800, v60
	s_waitcnt vmcnt(0)
	ds_write_b128 v107, v[204:207] offset:4352
	ds_write_b128 v107, v[208:211] offset:8704
	ds_write_b128 v107, v[216:219] offset:13056
	ds_write_b128 v107, v[220:223] offset:17408
	ds_write_b128 v107, v[224:227] offset:21760
	ds_write_b128 v107, v[228:231] offset:26112
	ds_write_b128 v107, v[232:235] offset:30464
	ds_write2_b32 v65, v67, v56 offset1:68
	v_and_b32_e32 v56, 0xffff, v57
	v_lshrrev_b32_e32 v57, 16, v57
	v_lshl_or_b32 v56, v61, 16, v56
	v_and_or_b32 v57, v61, s4, v57
	ds_write2_b32 v65, v56, v57 offset0:136 offset1:204
	v_and_b32_e32 v56, 0xffff, v58
	v_lshrrev_b32_e32 v57, 16, v58
	v_lshl_or_b32 v56, v62, 16, v56
	v_and_or_b32 v57, v62, s4, v57
	v_add_u32_e32 v58, 0x8c00, v60
	ds_write2_b32 v58, v56, v57 offset0:16 offset1:84
	v_and_b32_e32 v56, 0xffff, v59
	v_lshrrev_b32_e32 v57, 16, v59
	v_lshl_or_b32 v56, v63, 16, v56
	v_and_or_b32 v57, v63, s4, v57
	ds_write2_b32 v58, v56, v57 offset0:152 offset1:220
	v_and_b32_e32 v56, 0xffff, v48
	v_lshrrev_b32_e32 v48, 16, v48
	v_lshl_or_b32 v56, v52, 16, v56
	v_and_or_b32 v48, v52, s4, v48
	v_add_u32_e32 v52, 0x9000, v60
	ds_write2_b32 v52, v56, v48 offset0:32 offset1:100
	v_and_b32_e32 v48, 0xffff, v49
	v_lshrrev_b32_e32 v49, 16, v49
	v_lshl_or_b32 v48, v53, 16, v48
	v_and_or_b32 v49, v53, s4, v49
	ds_write2_b32 v52, v48, v49 offset0:168 offset1:236
	v_and_b32_e32 v48, 0xffff, v50
	v_lshrrev_b32_e32 v49, 16, v50
	v_lshl_or_b32 v48, v54, 16, v48
	v_and_or_b32 v49, v54, s4, v49
	v_add_u32_e32 v50, 0x9400, v60
	ds_write2_b32 v50, v48, v49 offset0:48 offset1:116
	v_and_b32_e32 v48, 0xffff, v51
	v_lshrrev_b32_e32 v49, 16, v51
	v_lshl_or_b32 v48, v55, 16, v48
	v_and_or_b32 v49, v55, s4, v49
	ds_write2_b32 v50, v48, v49 offset0:184 offset1:252
	v_and_b32_e32 v48, 0xffff, v40
	v_lshrrev_b32_e32 v40, 16, v40
	v_lshl_or_b32 v48, v44, 16, v48
	v_and_or_b32 v40, v44, s4, v40
	v_add_u32_e32 v44, 0x9800, v60
	ds_write2_b32 v44, v48, v40 offset0:64 offset1:132
	v_and_b32_e32 v40, 0xffff, v41
	v_lshrrev_b32_e32 v41, 16, v41
	v_lshl_or_b32 v40, v45, 16, v40
	v_and_or_b32 v41, v45, s4, v41
	v_add_u32_e32 v44, 0x9a00, v60
	ds_write2_b32 v44, v40, v41 offset0:72 offset1:140
	v_and_b32_e32 v40, 0xffff, v42
	v_lshrrev_b32_e32 v41, 16, v42
	v_lshl_or_b32 v40, v46, 16, v40
	v_and_or_b32 v41, v46, s4, v41
	v_add_u32_e32 v42, 0x9c00, v60
	ds_write2_b32 v42, v40, v41 offset0:80 offset1:148
	v_and_b32_e32 v40, 0xffff, v43
	v_lshrrev_b32_e32 v41, 16, v43
	v_lshl_or_b32 v40, v47, 16, v40
	v_and_or_b32 v41, v47, s4, v41
	v_add_u32_e32 v42, 0x9e00, v60
	ds_write2_b32 v42, v40, v41 offset0:88 offset1:156
	v_and_b32_e32 v40, 0xffff, v32
	v_lshrrev_b32_e32 v32, 16, v32
	v_lshl_or_b32 v40, v36, 16, v40
	v_and_or_b32 v32, v36, s4, v32
	v_add_u32_e32 v36, 0xa000, v60
	ds_write2_b32 v36, v40, v32 offset0:96 offset1:164
	v_and_b32_e32 v32, 0xffff, v33
	v_lshrrev_b32_e32 v33, 16, v33
	v_lshl_or_b32 v32, v37, 16, v32
	v_and_or_b32 v33, v37, s4, v33
	v_add_u32_e32 v36, 0xa200, v60
	ds_write2_b32 v36, v32, v33 offset0:104 offset1:172
	v_and_b32_e32 v32, 0xffff, v34
	v_lshrrev_b32_e32 v33, 16, v34
	v_lshl_or_b32 v32, v38, 16, v32
	v_and_or_b32 v33, v38, s4, v33
	v_add_u32_e32 v34, 0xa400, v60
	ds_write2_b32 v34, v32, v33 offset0:112 offset1:180
	v_lshrrev_b32_e32 v33, 16, v35
	v_and_b32_e32 v32, 0xffff, v35
	v_and_or_b32 v33, v39, s4, v33
	s_lshl_b64 s[4:5], s[70:71], 2
	v_lshl_or_b32 v32, v39, 16, v32
	v_add_u32_e32 v34, 0xa600, v60
	s_waitcnt lgkmcnt(0)
	s_add_u32 s4, s8, s4
	ds_write2_b32 v34, v32, v33 offset0:120 offset1:188
	s_addc_u32 s5, s9, s5
	global_load_dword v32, v129, s[4:5]
	global_load_dword v33, v165, s[4:5] offset:128
	s_waitcnt lgkmcnt(0)
	s_barrier
	s_and_saveexec_b64 s[4:5], vcc
	s_xor_b64 s[30:31], exec, s[4:5]
	s_cbranch_execz .LBB1_118
	s_movk_i32 s4, 0x100
	s_waitcnt vmcnt(1)
	v_add_u32_e32 v32, 0xffffff80, v64
	v_cmp_gt_u32_e32 vcc, s4, v64
	v_mov_b32_e32 v35, 0xff61b1e6
	v_mov_b32_e32 v34, 0
	v_mov_b32_e32 v38, 0
	s_and_saveexec_b64 s[38:39], vcc
	s_cbranch_execz .LBB1_117
	v_min_u32_e32 v34, 0x7f, v32
	v_sub_u32_e32 v36, 0x80, v34
	v_xor_b32_e32 v34, 0x7f, v34
	v_mov_b32_e32 v39, 0x7f
	v_cmp_lt_u32_e32 vcc, 6, v34
	v_mov_b32_e32 v34, 0
	v_mov_b32_e32 v35, 0xff61b1e6
	s_and_saveexec_b64 s[40:41], vcc
	s_cbranch_execz .LBB1_112
	v_and_b32_e32 v34, 0xf8, v36
	s_mov_b32 s5, 0
	v_sub_u32_e32 v37, 0, v34
	s_mov_b64 s[42:43], 0
	v_mov_b32_e32 v35, 0xff61b1e6
	v_mov_b32_e32 v34, 0
	v_readlane_b32 s4, v241, 17
